# cache policy: input-projection epilogue stores marked nt (write-once streaming h data, keep A/B panels in L2)
# baseline (speedup 1.0000x reference)
; __device__ __forceinline__ f32x4 sig4(f32x4 v) { return (f32x4){sigmoidf_(v[0]), sigmoidf_(v[1]), sigmoidf_(v[2]), sigmoidf_(v[3])}; }
; __device__ __forceinline__ f32x4 silu4(f32x4 v) { return v * sig4(v); }
; __device__ __forceinline__ u32x4 pack8(f32x4 a, f32x4 b) { u32x4 w; w.x = cvt_pk_bf16(a[0], a[1]); w.y = cvt_pk_bf16(a[2], a[3]); w.z = cvt_pk_bf16(b[0], b[1]); w.w = cvt_pk_bf16(b[2], b[3]); return w; }
;     template <int MODE> __device__ __forceinline__ void body(AccRef acc, int row0, size_t hc, int ld) const {
; #pragma unroll
;         for (int ai = 0; ai < 2; ++ai)
; #pragma unroll
;             for (int m = 0; m < 4; ++m) { bf16_t* rowp = H + (size_t)(row0 + ai * 128 + m * 16) * ld + hc;
; #pragma unroll
;                 for (int bj = 0; bj < 2; ++bj) { f32x4 v0 = acc[ai][bj][m][0], v1 = acc[ai][bj][m][1];
;                     if (MODE == 1) { v0 = silu4(v0); v1 = silu4(v1); }
;                     if (MODE == 2) { v0 = sig4(v0); v1 = sig4(v1); }
;                     *(u32x4*)(rowp + bj * 128) = pack8(v0, v1); } }
.LBB0_230:
	v_lshl_add_u32 v155, s3, 8, v152
	v_ashrrev_i32_e32 v144, 31, v155
	v_lshl_add_u64 v[142:143], s[22:23], 0, v[136:137]
	v_mul_lo_u32 v156, s18, v144
	v_mul_lo_u32 v146, s19, v155
	v_mad_u64_u32 v[144:145], s[22:23], s18, v155, 0
	v_add3_u32 v145, v145, v156, v146
	v_lshl_add_u64 v[144:145], v[144:145], 1, s[8:9]
	s_mov_b64 s[26:27], -1
	s_andn2_b64 vcc, exec, s[24:25]
	v_lshl_add_u64 v[144:145], v[142:143], 1, v[144:145]
	s_cbranch_vccz .LBB0_240
	s_xor_b64 s[22:23], s[4:5], -1
	s_mov_b64 s[4:5], -1
	s_and_b64 vcc, exec, s[22:23]
	s_cbranch_vccz .LBB0_237
	v_mul_f32_e32 v146, 0xbfb8aa3b, v120
	v_mul_f32_e32 v147, 0xbfb8aa3b, v121
	v_mul_f32_e32 v148, 0xbfb8aa3b, v122
	v_mul_f32_e32 v149, 0xbfb8aa3b, v123
	v_exp_f32_e32 v146, v146
	v_exp_f32_e32 v147, v147
	v_exp_f32_e32 v148, v148
	v_exp_f32_e32 v149, v149
	v_add_f32_e32 v146, 1.0, v146
	v_add_f32_e32 v147, 1.0, v147
	v_add_f32_e32 v148, 1.0, v148
	v_add_f32_e32 v149, 1.0, v149
	v_rcp_f32_e32 v146, v146
	v_rcp_f32_e32 v147, v147
	v_rcp_f32_e32 v148, v148
	v_rcp_f32_e32 v149, v149
	s_xor_b64 s[20:21], s[20:21], -1
	s_and_b64 vcc, exec, s[20:21]
	v_mul_f32_e32 v211, 0xbfb8aa3b, v112
	v_mul_f32_e32 v210, 0xbfb8aa3b, v113
	v_mul_f32_e32 v209, 0xbfb8aa3b, v114
	v_mul_f32_e32 v208, 0xbfb8aa3b, v115
	v_mul_f32_e32 v207, 0xbfb8aa3b, v104
	v_mul_f32_e32 v206, 0xbfb8aa3b, v105
	v_mul_f32_e32 v205, 0xbfb8aa3b, v106
	v_mul_f32_e32 v204, 0xbfb8aa3b, v107
	v_mul_f32_e32 v203, 0xbfb8aa3b, v96
	v_mul_f32_e32 v202, 0xbfb8aa3b, v97
	v_mul_f32_e32 v201, 0xbfb8aa3b, v98
	v_mul_f32_e32 v200, 0xbfb8aa3b, v99
	v_mul_f32_e32 v199, 0xbfb8aa3b, v88
	v_mul_f32_e32 v198, 0xbfb8aa3b, v89
	v_mul_f32_e32 v197, 0xbfb8aa3b, v90
	v_mul_f32_e32 v196, 0xbfb8aa3b, v91
	v_mul_f32_e32 v193, 0xbfb8aa3b, v80
	v_mul_f32_e32 v192, 0xbfb8aa3b, v81
	v_mul_f32_e32 v187, 0xbfb8aa3b, v82
	v_mul_f32_e32 v186, 0xbfb8aa3b, v83
	v_mul_f32_e32 v183, 0xbfb8aa3b, v72
	v_mul_f32_e32 v182, 0xbfb8aa3b, v73
	v_mul_f32_e32 v181, 0xbfb8aa3b, v74
	v_mul_f32_e32 v180, 0xbfb8aa3b, v75
	v_mul_f32_e32 v179, 0xbfb8aa3b, v64
	v_mul_f32_e32 v178, 0xbfb8aa3b, v65
	v_mul_f32_e32 v177, 0xbfb8aa3b, v66
	v_mul_f32_e32 v176, 0xbfb8aa3b, v67
	v_mul_f32_e32 v175, 0xbfb8aa3b, v56
	v_mul_f32_e32 v174, 0xbfb8aa3b, v57
	v_mul_f32_e32 v173, 0xbfb8aa3b, v58
	v_mul_f32_e32 v172, 0xbfb8aa3b, v59
	v_mul_f32_e32 v171, 0xbfb8aa3b, v48
	v_mul_f32_e32 v170, 0xbfb8aa3b, v49
	v_mul_f32_e32 v169, 0xbfb8aa3b, v50
	v_mul_f32_e32 v168, 0xbfb8aa3b, v51
	v_mul_f32_e32 v167, 0xbfb8aa3b, v40
	v_mul_f32_e32 v166, 0xbfb8aa3b, v41
	v_mul_f32_e32 v165, 0xbfb8aa3b, v42
	v_mul_f32_e32 v164, 0xbfb8aa3b, v43
	v_mul_f32_e32 v163, 0xbfb8aa3b, v32
	v_mul_f32_e32 v162, 0xbfb8aa3b, v33
	v_mul_f32_e32 v161, 0xbfb8aa3b, v34
	v_mul_f32_e32 v160, 0xbfb8aa3b, v35
	v_mul_f32_e32 v159, 0xbfb8aa3b, v24
	v_mul_f32_e32 v158, 0xbfb8aa3b, v25
	v_mul_f32_e32 v157, 0xbfb8aa3b, v26
	s_cbranch_vccz .LBB0_234
	v_exp_f32_e32 v212, v209
	v_exp_f32_e32 v150, v211
	v_exp_f32_e32 v151, v210
	v_exp_f32_e32 v213, v208
	v_add_f32_e32 v212, 1.0, v212
	v_add_f32_e32 v150, 1.0, v150
	v_add_f32_e32 v151, 1.0, v151
	v_rcp_f32_e32 v215, v212
	v_add_f32_e32 v212, 1.0, v213
	v_rcp_f32_e32 v150, v150
	v_rcp_f32_e32 v151, v151
	v_rcp_f32_e32 v216, v212
	v_cvt_pk_bf16_f32 v212, v146, v147
	v_cvt_pk_bf16_f32 v213, v148, v149
	v_cvt_pk_bf16_f32 v214, v150, v151
	v_cvt_pk_bf16_f32 v215, v215, v216
	global_store_dwordx4 v[144:145], v[212:215], off nt
	v_mul_f32_e32 v150, 0xbfb8aa3b, v124
	v_mul_f32_e32 v151, 0xbfb8aa3b, v125
	v_mul_f32_e32 v212, 0xbfb8aa3b, v126
	v_exp_f32_e32 v212, v212
	v_mul_f32_e32 v213, 0xbfb8aa3b, v127
	v_exp_f32_e32 v213, v213
	v_mul_f32_e32 v215, 0xbfb8aa3b, v117
	v_add_f32_e32 v212, 1.0, v212
	v_rcp_f32_e32 v214, v212
	v_add_f32_e32 v212, 1.0, v213
	v_mul_f32_e32 v213, 0xbfb8aa3b, v116
	v_exp_f32_e32 v213, v213
	v_exp_f32_e32 v215, v215
	v_rcp_f32_e32 v216, v212
	v_exp_f32_e32 v150, v150
	v_add_f32_e32 v212, 1.0, v213
	v_mul_f32_e32 v213, 0xbfb8aa3b, v118
	v_rcp_f32_e32 v217, v212
	v_add_f32_e32 v212, 1.0, v215
	v_exp_f32_e32 v213, v213
	v_mul_f32_e32 v215, 0xbfb8aa3b, v119
	v_exp_f32_e32 v151, v151
	v_exp_f32_e32 v215, v215
	v_rcp_f32_e32 v218, v212
	v_add_f32_e32 v212, 1.0, v213
	v_add_f32_e32 v150, 1.0, v150
	v_add_f32_e32 v151, 1.0, v151
	v_rcp_f32_e32 v219, v212
	v_add_f32_e32 v212, 1.0, v215
	v_rcp_f32_e32 v150, v150
	v_rcp_f32_e32 v151, v151
	v_rcp_f32_e32 v215, v212
	v_cvt_pk_bf16_f32 v213, v214, v216
	v_cvt_pk_bf16_f32 v214, v217, v218
	v_cvt_pk_bf16_f32 v212, v150, v151
	v_cvt_pk_bf16_f32 v215, v219, v215
	global_store_dwordx4 v[144:145], v[212:215], off offset:256 nt
	v_or_b32_e32 v150, 16, v155
	v_exp_f32_e32 v218, v203
	v_exp_f32_e32 v214, v207
	v_mul_lo_u32 v212, s19, v150
	v_mad_u64_u32 v[150:151], s[4:5], s18, v150, 0
	v_add3_u32 v151, v151, v156, v212
	v_lshl_add_u64 v[212:213], v[150:151], 1, s[8:9]
	v_lshlrev_b64 v[150:151], 1, v[142:143]
	v_lshl_add_u64 v[216:217], v[212:213], 0, v[150:151]
	v_exp_f32_e32 v212, v206
	v_add_f32_e32 v213, 1.0, v214
	v_exp_f32_e32 v214, v205
	v_exp_f32_e32 v215, v204
	v_exp_f32_e32 v219, v202
	v_add_f32_e32 v212, 1.0, v212
	v_add_f32_e32 v214, 1.0, v214
	v_add_f32_e32 v215, 1.0, v215
	v_add_f32_e32 v218, 1.0, v218
	v_exp_f32_e32 v220, v201
	v_add_f32_e32 v219, 1.0, v219
	v_exp_f32_e32 v221, v200
	v_rcp_f32_e32 v213, v213
	v_rcp_f32_e32 v212, v212
	v_rcp_f32_e32 v214, v214
	v_rcp_f32_e32 v215, v215
	v_rcp_f32_e32 v218, v218
	v_rcp_f32_e32 v219, v219
	v_add_f32_e32 v220, 1.0, v220
	v_add_f32_e32 v221, 1.0, v221
	v_rcp_f32_e32 v220, v220
	v_rcp_f32_e32 v221, v221
	v_cvt_pk_bf16_f32 v212, v213, v212
	v_cvt_pk_bf16_f32 v213, v214, v215
; __device__ __forceinline__ f32x4 sig4(f32x4 v) { return (f32x4){sigmoidf_(v[0]), sigmoidf_(v[1]), sigmoidf_(v[2]), sigmoidf_(v[3])}; }
; __device__ __forceinline__ f32x4 silu4(f32x4 v) { return v * sig4(v); }
; __device__ __forceinline__ u32x4 pack8(f32x4 a, f32x4 b) { u32x4 w; w.x = cvt_pk_bf16(a[0], a[1]); w.y = cvt_pk_bf16(a[2], a[3]); w.z = cvt_pk_bf16(b[0], b[1]); w.w = cvt_pk_bf16(b[2], b[3]); return w; }
;     template <int MODE> __device__ __forceinline__ void body(AccRef acc, int row0, size_t hc, int ld) const {
; #pragma unroll
;         for (int ai = 0; ai < 2; ++ai)
; #pragma unroll
;             for (int m = 0; m < 4; ++m) { bf16_t* rowp = H + (size_t)(row0 + ai * 128 + m * 16) * ld + hc;
; #pragma unroll
;                 for (int bj = 0; bj < 2; ++bj) { f32x4 v0 = acc[ai][bj][m][0], v1 = acc[ai][bj][m][1];
;                     if (MODE == 1) { v0 = silu4(v0); v1 = silu4(v1); }
;                     if (MODE == 2) { v0 = sig4(v0); v1 = sig4(v1); }
;                     *(u32x4*)(rowp + bj * 128) = pack8(v0, v1); } }
	v_cvt_pk_bf16_f32 v214, v218, v219
	v_mul_f32_e32 v218, 0xbfb8aa3b, v108
	v_mul_f32_e32 v219, 0xbfb8aa3b, v109
	v_exp_f32_e32 v218, v218
	v_exp_f32_e32 v219, v219
	v_cvt_pk_bf16_f32 v215, v220, v221
	global_store_dwordx4 v[216:217], v[212:215], off nt
	v_mul_f32_e32 v220, 0xbfb8aa3b, v102
	v_mul_f32_e32 v221, 0xbfb8aa3b, v103
	v_add_f32_e32 v212, 1.0, v218
	v_add_f32_e32 v213, 1.0, v219
	v_mul_f32_e32 v214, 0xbfb8aa3b, v110
	v_mul_f32_e32 v215, 0xbfb8aa3b, v111
	v_mul_f32_e32 v218, 0xbfb8aa3b, v100
	v_mul_f32_e32 v219, 0xbfb8aa3b, v101
	v_exp_f32_e32 v214, v214
	v_exp_f32_e32 v215, v215
	v_exp_f32_e32 v218, v218
	v_exp_f32_e32 v219, v219
	v_exp_f32_e32 v220, v220
	v_exp_f32_e32 v221, v221
	v_add_f32_e32 v214, 1.0, v214
	v_add_f32_e32 v215, 1.0, v215
	v_add_f32_e32 v218, 1.0, v218
	v_add_f32_e32 v219, 1.0, v219
	v_add_f32_e32 v220, 1.0, v220
	v_add_f32_e32 v221, 1.0, v221
	v_rcp_f32_e32 v212, v212
	v_rcp_f32_e32 v213, v213
	v_rcp_f32_e32 v214, v214
	v_rcp_f32_e32 v215, v215
	v_rcp_f32_e32 v218, v218
	v_rcp_f32_e32 v219, v219
	v_rcp_f32_e32 v220, v220
	v_rcp_f32_e32 v221, v221
	v_cvt_pk_bf16_f32 v212, v212, v213
	v_cvt_pk_bf16_f32 v213, v214, v215
	v_cvt_pk_bf16_f32 v214, v218, v219
	v_cvt_pk_bf16_f32 v215, v220, v221
	global_store_dwordx4 v[216:217], v[212:215], off offset:256 nt
	v_exp_f32_e32 v218, v193
	v_exp_f32_e32 v219, v192
	v_or_b32_e32 v212, 32, v155
	v_mul_lo_u32 v214, s19, v212
	v_mad_u64_u32 v[212:213], s[4:5], s18, v212, 0
	v_add3_u32 v213, v213, v156, v214
	v_exp_f32_e32 v214, v199
	v_lshl_add_u64 v[212:213], v[212:213], 1, s[8:9]
	v_lshl_add_u64 v[216:217], v[212:213], 0, v[150:151]
	v_exp_f32_e32 v212, v198
	v_add_f32_e32 v213, 1.0, v214
	v_exp_f32_e32 v214, v197
	v_exp_f32_e32 v215, v196
	v_add_f32_e32 v212, 1.0, v212
	v_add_f32_e32 v218, 1.0, v218
	v_add_f32_e32 v214, 1.0, v214
	v_add_f32_e32 v215, 1.0, v215
	v_exp_f32_e32 v220, v187
	v_add_f32_e32 v219, 1.0, v219
	v_exp_f32_e32 v221, v186
	v_rcp_f32_e32 v213, v213
	v_rcp_f32_e32 v212, v212
	v_rcp_f32_e32 v214, v214
	v_rcp_f32_e32 v215, v215
	v_rcp_f32_e32 v218, v218
	v_rcp_f32_e32 v219, v219
	v_add_f32_e32 v220, 1.0, v220
	v_add_f32_e32 v221, 1.0, v221
	v_rcp_f32_e32 v220, v220
	v_rcp_f32_e32 v221, v221
	v_cvt_pk_bf16_f32 v212, v213, v212
	v_cvt_pk_bf16_f32 v213, v214, v215
	v_cvt_pk_bf16_f32 v214, v218, v219
	v_mul_f32_e32 v218, 0xbfb8aa3b, v92
	v_mul_f32_e32 v219, 0xbfb8aa3b, v93
	v_exp_f32_e32 v218, v218
	v_exp_f32_e32 v219, v219
	v_cvt_pk_bf16_f32 v215, v220, v221
	global_store_dwordx4 v[216:217], v[212:215], off nt
	v_mul_f32_e32 v220, 0xbfb8aa3b, v86
	v_mul_f32_e32 v221, 0xbfb8aa3b, v87
	v_add_f32_e32 v212, 1.0, v218
	v_add_f32_e32 v213, 1.0, v219
	v_mul_f32_e32 v214, 0xbfb8aa3b, v94
	v_mul_f32_e32 v215, 0xbfb8aa3b, v95
	v_mul_f32_e32 v218, 0xbfb8aa3b, v84
	v_mul_f32_e32 v219, 0xbfb8aa3b, v85
	v_exp_f32_e32 v214, v214
	v_exp_f32_e32 v215, v215
	v_exp_f32_e32 v218, v218
	v_exp_f32_e32 v219, v219
	v_exp_f32_e32 v220, v220
	v_exp_f32_e32 v221, v221
	v_add_f32_e32 v214, 1.0, v214
	v_add_f32_e32 v215, 1.0, v215
	v_add_f32_e32 v218, 1.0, v218
	v_add_f32_e32 v219, 1.0, v219
	v_add_f32_e32 v220, 1.0, v220
	v_add_f32_e32 v221, 1.0, v221
	v_rcp_f32_e32 v212, v212
	v_rcp_f32_e32 v213, v213
	v_rcp_f32_e32 v214, v214
	v_rcp_f32_e32 v215, v215
	v_rcp_f32_e32 v218, v218
	v_rcp_f32_e32 v219, v219
	v_rcp_f32_e32 v220, v220
	v_rcp_f32_e32 v221, v221
	v_cvt_pk_bf16_f32 v212, v212, v213
	v_cvt_pk_bf16_f32 v213, v214, v215
	v_cvt_pk_bf16_f32 v214, v218, v219
	v_cvt_pk_bf16_f32 v215, v220, v221
	global_store_dwordx4 v[216:217], v[212:215], off offset:256 nt
	v_exp_f32_e32 v218, v179
	v_exp_f32_e32 v219, v178
	v_or_b32_e32 v212, 48, v155
	v_mul_lo_u32 v214, s19, v212
	v_mad_u64_u32 v[212:213], s[4:5], s18, v212, 0
	v_add3_u32 v213, v213, v156, v214
	v_exp_f32_e32 v214, v183
	v_lshl_add_u64 v[212:213], v[212:213], 1, s[8:9]
	v_lshl_add_u64 v[216:217], v[212:213], 0, v[150:151]
	v_exp_f32_e32 v212, v182
	v_add_f32_e32 v213, 1.0, v214
	v_exp_f32_e32 v214, v181
	v_exp_f32_e32 v215, v180
	v_add_f32_e32 v212, 1.0, v212
	v_add_f32_e32 v218, 1.0, v218
	v_add_f32_e32 v214, 1.0, v214
	v_add_f32_e32 v215, 1.0, v215
	v_exp_f32_e32 v220, v177
	v_add_f32_e32 v219, 1.0, v219
	v_exp_f32_e32 v221, v176
	v_rcp_f32_e32 v213, v213
	v_rcp_f32_e32 v212, v212
	v_rcp_f32_e32 v214, v214
	v_rcp_f32_e32 v215, v215
	v_rcp_f32_e32 v218, v218
	v_rcp_f32_e32 v219, v219
	v_add_f32_e32 v220, 1.0, v220
	v_add_f32_e32 v221, 1.0, v221
	v_rcp_f32_e32 v220, v220
	v_rcp_f32_e32 v221, v221
	v_cvt_pk_bf16_f32 v212, v213, v212
	v_cvt_pk_bf16_f32 v213, v214, v215
	v_cvt_pk_bf16_f32 v214, v218, v219
	v_mul_f32_e32 v218, 0xbfb8aa3b, v76
	v_mul_f32_e32 v219, 0xbfb8aa3b, v77
	v_exp_f32_e32 v218, v218
	v_exp_f32_e32 v219, v219
	v_cvt_pk_bf16_f32 v215, v220, v221
	global_store_dwordx4 v[216:217], v[212:215], off nt
	v_mul_f32_e32 v220, 0xbfb8aa3b, v70
	v_mul_f32_e32 v221, 0xbfb8aa3b, v71
	v_add_f32_e32 v212, 1.0, v218
	v_add_f32_e32 v213, 1.0, v219
	v_mul_f32_e32 v214, 0xbfb8aa3b, v78
	v_mul_f32_e32 v215, 0xbfb8aa3b, v79
	v_mul_f32_e32 v218, 0xbfb8aa3b, v68
	v_mul_f32_e32 v219, 0xbfb8aa3b, v69
	v_exp_f32_e32 v214, v214
	v_exp_f32_e32 v215, v215
	v_exp_f32_e32 v218, v218
	v_exp_f32_e32 v219, v219
	v_exp_f32_e32 v220, v220
	v_exp_f32_e32 v221, v221
	v_add_f32_e32 v214, 1.0, v214
	v_add_f32_e32 v215, 1.0, v215
	v_add_f32_e32 v218, 1.0, v218
	v_add_f32_e32 v219, 1.0, v219
	v_add_f32_e32 v220, 1.0, v220
	v_add_f32_e32 v221, 1.0, v221
	v_rcp_f32_e32 v212, v212
	v_rcp_f32_e32 v213, v213
	v_rcp_f32_e32 v214, v214
	v_rcp_f32_e32 v215, v215
	v_rcp_f32_e32 v218, v218
	v_rcp_f32_e32 v219, v219
	v_rcp_f32_e32 v220, v220
	v_rcp_f32_e32 v221, v221
; __device__ __forceinline__ f32x4 sig4(f32x4 v) { return (f32x4){sigmoidf_(v[0]), sigmoidf_(v[1]), sigmoidf_(v[2]), sigmoidf_(v[3])}; }
; __device__ __forceinline__ f32x4 silu4(f32x4 v) { return v * sig4(v); }
; __device__ __forceinline__ u32x4 pack8(f32x4 a, f32x4 b) { u32x4 w; w.x = cvt_pk_bf16(a[0], a[1]); w.y = cvt_pk_bf16(a[2], a[3]); w.z = cvt_pk_bf16(b[0], b[1]); w.w = cvt_pk_bf16(b[2], b[3]); return w; }
;     template <int MODE> __device__ __forceinline__ void body(AccRef acc, int row0, size_t hc, int ld) const {
; #pragma unroll
;         for (int ai = 0; ai < 2; ++ai)
; #pragma unroll
;             for (int m = 0; m < 4; ++m) { bf16_t* rowp = H + (size_t)(row0 + ai * 128 + m * 16) * ld + hc;
; #pragma unroll
;                 for (int bj = 0; bj < 2; ++bj) { f32x4 v0 = acc[ai][bj][m][0], v1 = acc[ai][bj][m][1];
;                     if (MODE == 1) { v0 = silu4(v0); v1 = silu4(v1); }
;                     if (MODE == 2) { v0 = sig4(v0); v1 = sig4(v1); }
;                     *(u32x4*)(rowp + bj * 128) = pack8(v0, v1); } }
	v_cvt_pk_bf16_f32 v212, v212, v213
	v_cvt_pk_bf16_f32 v213, v214, v215
	v_cvt_pk_bf16_f32 v214, v218, v219
	v_cvt_pk_bf16_f32 v215, v220, v221
	global_store_dwordx4 v[216:217], v[212:215], off offset:256 nt
	v_exp_f32_e32 v218, v171
	v_exp_f32_e32 v219, v170
	v_add_u32_e32 v212, 0x80, v155
	v_ashrrev_i32_e32 v213, 31, v212
	v_mul_lo_u32 v214, s18, v213
	v_mul_lo_u32 v215, s19, v212
	v_mad_u64_u32 v[212:213], s[4:5], s18, v212, 0
	v_add3_u32 v213, v213, v214, v215
	v_exp_f32_e32 v214, v175
	v_lshl_add_u64 v[212:213], v[212:213], 1, s[8:9]
	v_lshl_add_u64 v[216:217], v[212:213], 0, v[150:151]
	v_exp_f32_e32 v212, v174
	v_add_f32_e32 v213, 1.0, v214
	v_exp_f32_e32 v214, v173
	v_exp_f32_e32 v215, v172
	v_add_f32_e32 v212, 1.0, v212
	v_add_f32_e32 v218, 1.0, v218
	v_add_f32_e32 v214, 1.0, v214
	v_add_f32_e32 v215, 1.0, v215
	v_exp_f32_e32 v220, v169
	v_add_f32_e32 v219, 1.0, v219
	v_exp_f32_e32 v221, v168
	v_rcp_f32_e32 v213, v213
	v_rcp_f32_e32 v212, v212
	v_rcp_f32_e32 v214, v214
	v_rcp_f32_e32 v215, v215
	v_rcp_f32_e32 v218, v218
	v_rcp_f32_e32 v219, v219
	v_add_f32_e32 v220, 1.0, v220
	v_add_f32_e32 v221, 1.0, v221
	v_rcp_f32_e32 v220, v220
	v_rcp_f32_e32 v221, v221
	v_cvt_pk_bf16_f32 v212, v213, v212
	v_cvt_pk_bf16_f32 v213, v214, v215
	v_cvt_pk_bf16_f32 v214, v218, v219
	v_mul_f32_e32 v218, 0xbfb8aa3b, v60
	v_mul_f32_e32 v219, 0xbfb8aa3b, v61
	v_exp_f32_e32 v218, v218
	v_exp_f32_e32 v219, v219
	v_cvt_pk_bf16_f32 v215, v220, v221
	global_store_dwordx4 v[216:217], v[212:215], off nt
	v_mul_f32_e32 v220, 0xbfb8aa3b, v54
	v_mul_f32_e32 v221, 0xbfb8aa3b, v55
	v_add_f32_e32 v212, 1.0, v218
	v_add_f32_e32 v213, 1.0, v219
	v_mul_f32_e32 v214, 0xbfb8aa3b, v62
	v_mul_f32_e32 v215, 0xbfb8aa3b, v63
	v_mul_f32_e32 v218, 0xbfb8aa3b, v52
	v_mul_f32_e32 v219, 0xbfb8aa3b, v53
	v_exp_f32_e32 v214, v214
	v_exp_f32_e32 v215, v215
	v_exp_f32_e32 v218, v218
	v_exp_f32_e32 v219, v219
	v_exp_f32_e32 v220, v220
	v_exp_f32_e32 v221, v221
	v_add_f32_e32 v214, 1.0, v214
	v_add_f32_e32 v215, 1.0, v215
	v_add_f32_e32 v218, 1.0, v218
	v_add_f32_e32 v219, 1.0, v219
	v_add_f32_e32 v220, 1.0, v220
	v_add_f32_e32 v221, 1.0, v221
	v_rcp_f32_e32 v212, v212
	v_rcp_f32_e32 v213, v213
	v_rcp_f32_e32 v214, v214
	v_rcp_f32_e32 v215, v215
	v_rcp_f32_e32 v218, v218
	v_rcp_f32_e32 v219, v219
	v_rcp_f32_e32 v220, v220
	v_rcp_f32_e32 v221, v221
	v_cvt_pk_bf16_f32 v212, v212, v213
	v_cvt_pk_bf16_f32 v213, v214, v215
	v_cvt_pk_bf16_f32 v214, v218, v219
	v_cvt_pk_bf16_f32 v215, v220, v221
	global_store_dwordx4 v[216:217], v[212:215], off offset:256 nt
	v_exp_f32_e32 v218, v163
	v_exp_f32_e32 v219, v162
	v_add_u32_e32 v212, 0x90, v155
	v_ashrrev_i32_e32 v213, 31, v212
	v_mul_lo_u32 v214, s18, v213
	v_mul_lo_u32 v215, s19, v212
	v_mad_u64_u32 v[212:213], s[4:5], s18, v212, 0
	v_add3_u32 v213, v213, v214, v215
	v_exp_f32_e32 v214, v167
	v_lshl_add_u64 v[212:213], v[212:213], 1, s[8:9]
	v_lshl_add_u64 v[216:217], v[212:213], 0, v[150:151]
	v_exp_f32_e32 v212, v166
	v_add_f32_e32 v213, 1.0, v214
	v_exp_f32_e32 v214, v165
	v_exp_f32_e32 v215, v164
	v_add_f32_e32 v212, 1.0, v212
	v_add_f32_e32 v218, 1.0, v218
	v_add_f32_e32 v214, 1.0, v214
	v_add_f32_e32 v215, 1.0, v215
	v_exp_f32_e32 v220, v161
	v_add_f32_e32 v219, 1.0, v219
	v_exp_f32_e32 v221, v160
	v_rcp_f32_e32 v213, v213
	v_rcp_f32_e32 v212, v212
	v_rcp_f32_e32 v214, v214
	v_rcp_f32_e32 v215, v215
	v_rcp_f32_e32 v218, v218
	v_rcp_f32_e32 v219, v219
	v_add_f32_e32 v220, 1.0, v220
	v_add_f32_e32 v221, 1.0, v221
	v_rcp_f32_e32 v220, v220
	v_rcp_f32_e32 v221, v221
	v_cvt_pk_bf16_f32 v212, v213, v212
	v_cvt_pk_bf16_f32 v213, v214, v215
	v_cvt_pk_bf16_f32 v214, v218, v219
	v_mul_f32_e32 v218, 0xbfb8aa3b, v44
	v_mul_f32_e32 v219, 0xbfb8aa3b, v45
	v_exp_f32_e32 v218, v218
	v_exp_f32_e32 v219, v219
	v_cvt_pk_bf16_f32 v215, v220, v221
	global_store_dwordx4 v[216:217], v[212:215], off nt
	v_mul_f32_e32 v220, 0xbfb8aa3b, v38
	v_mul_f32_e32 v221, 0xbfb8aa3b, v39
	v_add_f32_e32 v212, 1.0, v218
	v_add_f32_e32 v213, 1.0, v219
	v_mul_f32_e32 v214, 0xbfb8aa3b, v46
	v_mul_f32_e32 v215, 0xbfb8aa3b, v47
	v_mul_f32_e32 v218, 0xbfb8aa3b, v36
	v_mul_f32_e32 v219, 0xbfb8aa3b, v37
	v_exp_f32_e32 v214, v214
	v_exp_f32_e32 v215, v215
	v_exp_f32_e32 v218, v218
	v_exp_f32_e32 v219, v219
	v_exp_f32_e32 v220, v220
	v_exp_f32_e32 v221, v221
	v_add_f32_e32 v214, 1.0, v214
	v_add_f32_e32 v215, 1.0, v215
	v_add_f32_e32 v218, 1.0, v218
	v_add_f32_e32 v219, 1.0, v219
	v_add_f32_e32 v220, 1.0, v220
	v_add_f32_e32 v221, 1.0, v221
	v_rcp_f32_e32 v212, v212
	v_rcp_f32_e32 v213, v213
	v_rcp_f32_e32 v214, v214
	v_rcp_f32_e32 v215, v215
	v_rcp_f32_e32 v218, v218
	v_rcp_f32_e32 v219, v219
	v_rcp_f32_e32 v220, v220
	v_rcp_f32_e32 v221, v221
	v_cvt_pk_bf16_f32 v212, v212, v213
	v_cvt_pk_bf16_f32 v213, v214, v215
	v_cvt_pk_bf16_f32 v214, v218, v219
	v_cvt_pk_bf16_f32 v215, v220, v221
	global_store_dwordx4 v[216:217], v[212:215], off offset:256 nt
	v_mul_f32_e32 v218, 0xbfb8aa3b, v16
	v_mul_f32_e32 v219, 0xbfb8aa3b, v17
	v_add_u32_e32 v212, 0xa0, v155
	v_ashrrev_i32_e32 v213, 31, v212
	v_mul_lo_u32 v214, s18, v213
	v_mul_lo_u32 v215, s19, v212
	v_mad_u64_u32 v[212:213], s[4:5], s18, v212, 0
	v_add3_u32 v213, v213, v214, v215
	v_exp_f32_e32 v215, v158
	v_exp_f32_e32 v214, v159
	v_lshl_add_u64 v[212:213], v[212:213], 1, s[8:9]
	v_lshl_add_u64 v[216:217], v[212:213], 0, v[150:151]
	v_add_f32_e32 v213, 1.0, v215
	v_mul_f32_e32 v215, 0xbfb8aa3b, v27
	v_add_f32_e32 v212, 1.0, v214
	v_exp_f32_e32 v214, v157
	v_exp_f32_e32 v215, v215
	v_exp_f32_e32 v218, v218
	v_exp_f32_e32 v219, v219
	v_mul_f32_e32 v220, 0xbfb8aa3b, v18
	v_mul_f32_e32 v221, 0xbfb8aa3b, v19
	v_add_f32_e32 v214, 1.0, v214
; __device__ __forceinline__ f32x4 sig4(f32x4 v) { return (f32x4){sigmoidf_(v[0]), sigmoidf_(v[1]), sigmoidf_(v[2]), sigmoidf_(v[3])}; }
; __device__ __forceinline__ f32x4 silu4(f32x4 v) { return v * sig4(v); }
; __device__ __forceinline__ u32x4 pack8(f32x4 a, f32x4 b) { u32x4 w; w.x = cvt_pk_bf16(a[0], a[1]); w.y = cvt_pk_bf16(a[2], a[3]); w.z = cvt_pk_bf16(b[0], b[1]); w.w = cvt_pk_bf16(b[2], b[3]); return w; }
;     template <int MODE> __device__ __forceinline__ void body(AccRef acc, int row0, size_t hc, int ld) const {
; #pragma unroll
;         for (int ai = 0; ai < 2; ++ai)
; #pragma unroll
;             for (int m = 0; m < 4; ++m) { bf16_t* rowp = H + (size_t)(row0 + ai * 128 + m * 16) * ld + hc;
; #pragma unroll
;                 for (int bj = 0; bj < 2; ++bj) { f32x4 v0 = acc[ai][bj][m][0], v1 = acc[ai][bj][m][1];
;                     if (MODE == 1) { v0 = silu4(v0); v1 = silu4(v1); }
;                     if (MODE == 2) { v0 = sig4(v0); v1 = sig4(v1); }
;                     *(u32x4*)(rowp + bj * 128) = pack8(v0, v1); } }
	v_add_f32_e32 v215, 1.0, v215
	v_add_f32_e32 v218, 1.0, v218
	v_add_f32_e32 v219, 1.0, v219
	v_exp_f32_e32 v220, v220
	v_exp_f32_e32 v221, v221
	v_rcp_f32_e32 v212, v212
	v_rcp_f32_e32 v213, v213
	v_rcp_f32_e32 v214, v214
	v_rcp_f32_e32 v215, v215
	v_rcp_f32_e32 v218, v218
	v_rcp_f32_e32 v219, v219
	v_add_f32_e32 v220, 1.0, v220
	v_add_f32_e32 v221, 1.0, v221
	v_rcp_f32_e32 v220, v220
	v_rcp_f32_e32 v221, v221
	v_cvt_pk_bf16_f32 v212, v212, v213
	v_cvt_pk_bf16_f32 v213, v214, v215
	v_cvt_pk_bf16_f32 v214, v218, v219
	v_mul_f32_e32 v218, 0xbfb8aa3b, v28
	v_mul_f32_e32 v219, 0xbfb8aa3b, v29
	v_exp_f32_e32 v218, v218
	v_exp_f32_e32 v219, v219
	v_cvt_pk_bf16_f32 v215, v220, v221
	global_store_dwordx4 v[216:217], v[212:215], off nt
	v_mul_f32_e32 v220, 0xbfb8aa3b, v22
	v_mul_f32_e32 v221, 0xbfb8aa3b, v23
	v_add_f32_e32 v212, 1.0, v218
	v_add_f32_e32 v213, 1.0, v219
	v_mul_f32_e32 v214, 0xbfb8aa3b, v30
	v_mul_f32_e32 v215, 0xbfb8aa3b, v31
	v_mul_f32_e32 v218, 0xbfb8aa3b, v20
	v_mul_f32_e32 v219, 0xbfb8aa3b, v21
	v_exp_f32_e32 v214, v214
	v_exp_f32_e32 v215, v215
	v_exp_f32_e32 v218, v218
	v_exp_f32_e32 v219, v219
	v_exp_f32_e32 v220, v220
	v_exp_f32_e32 v221, v221
	v_add_f32_e32 v214, 1.0, v214
	v_add_f32_e32 v215, 1.0, v215
	v_add_f32_e32 v218, 1.0, v218
	v_add_f32_e32 v219, 1.0, v219
	v_add_f32_e32 v220, 1.0, v220
	v_add_f32_e32 v221, 1.0, v221
	v_rcp_f32_e32 v212, v212
	v_rcp_f32_e32 v213, v213
	v_rcp_f32_e32 v214, v214
	v_rcp_f32_e32 v215, v215
	v_rcp_f32_e32 v218, v218
	v_rcp_f32_e32 v219, v219
	v_rcp_f32_e32 v220, v220
	v_rcp_f32_e32 v221, v221
	v_cvt_pk_bf16_f32 v212, v212, v213
	v_cvt_pk_bf16_f32 v213, v214, v215
	v_cvt_pk_bf16_f32 v214, v218, v219
	v_cvt_pk_bf16_f32 v215, v220, v221
	global_store_dwordx4 v[216:217], v[212:215], off offset:256 nt
	v_mul_f32_e32 v216, 0xbfb8aa3b, v0
	v_mul_f32_e32 v217, 0xbfb8aa3b, v1
	v_add_u32_e32 v212, 0xb0, v155
	v_ashrrev_i32_e32 v213, 31, v212
	v_mul_lo_u32 v214, s18, v213
	v_mul_lo_u32 v215, s19, v212
	v_mad_u64_u32 v[212:213], s[4:5], s18, v212, 0
	v_add3_u32 v213, v213, v214, v215
	v_mul_f32_e32 v214, 0xbfb8aa3b, v4
	v_mul_f32_e32 v215, 0xbfb8aa3b, v5
	v_exp_f32_e32 v214, v214
	v_exp_f32_e32 v215, v215
	v_lshl_add_u64 v[212:213], v[212:213], 1, s[8:9]
	v_lshl_add_u64 v[150:151], v[212:213], 0, v[150:151]
	v_add_f32_e32 v212, 1.0, v214
	v_add_f32_e32 v213, 1.0, v215
	v_mul_f32_e32 v214, 0xbfb8aa3b, v6
	v_mul_f32_e32 v215, 0xbfb8aa3b, v7
	v_exp_f32_e32 v214, v214
	v_exp_f32_e32 v215, v215
	v_exp_f32_e32 v216, v216
	v_exp_f32_e32 v217, v217
	v_mul_f32_e32 v218, 0xbfb8aa3b, v2
	v_mul_f32_e32 v219, 0xbfb8aa3b, v3
	v_add_f32_e32 v214, 1.0, v214
	v_add_f32_e32 v215, 1.0, v215
	v_add_f32_e32 v216, 1.0, v216
	v_add_f32_e32 v217, 1.0, v217
	v_exp_f32_e32 v218, v218
	v_exp_f32_e32 v219, v219
	v_rcp_f32_e32 v212, v212
	v_rcp_f32_e32 v213, v213
	v_rcp_f32_e32 v214, v214
	v_rcp_f32_e32 v215, v215
	v_rcp_f32_e32 v216, v216
	v_rcp_f32_e32 v217, v217
	v_add_f32_e32 v218, 1.0, v218
	v_add_f32_e32 v219, 1.0, v219
	v_rcp_f32_e32 v218, v218
	v_rcp_f32_e32 v219, v219
	v_cvt_pk_bf16_f32 v212, v212, v213
	v_cvt_pk_bf16_f32 v213, v214, v215
	v_cvt_pk_bf16_f32 v214, v216, v217
	v_mul_f32_e32 v216, 0xbfb8aa3b, v12
	v_mul_f32_e32 v217, 0xbfb8aa3b, v13
	v_exp_f32_e32 v216, v216
	v_exp_f32_e32 v217, v217
	v_cvt_pk_bf16_f32 v215, v218, v219
	global_store_dwordx4 v[150:151], v[212:215], off nt
	v_mul_f32_e32 v218, 0xbfb8aa3b, v10
	v_mul_f32_e32 v219, 0xbfb8aa3b, v11
	v_add_f32_e32 v212, 1.0, v216
	v_add_f32_e32 v213, 1.0, v217
	v_mul_f32_e32 v214, 0xbfb8aa3b, v14
	v_mul_f32_e32 v215, 0xbfb8aa3b, v15
	v_mul_f32_e32 v216, 0xbfb8aa3b, v8
	v_mul_f32_e32 v217, 0xbfb8aa3b, v9
	v_exp_f32_e32 v214, v214
	v_exp_f32_e32 v215, v215
	v_exp_f32_e32 v216, v216
	v_exp_f32_e32 v217, v217
	v_exp_f32_e32 v218, v218
	v_exp_f32_e32 v219, v219
	v_add_f32_e32 v214, 1.0, v214
	v_add_f32_e32 v215, 1.0, v215
	v_add_f32_e32 v216, 1.0, v216
	v_add_f32_e32 v217, 1.0, v217
	v_add_f32_e32 v218, 1.0, v218
	v_add_f32_e32 v219, 1.0, v219
	v_rcp_f32_e32 v212, v212
	v_rcp_f32_e32 v213, v213
	v_rcp_f32_e32 v214, v214
	v_rcp_f32_e32 v215, v215
	v_rcp_f32_e32 v216, v216
	v_rcp_f32_e32 v217, v217
	v_rcp_f32_e32 v218, v218
	v_rcp_f32_e32 v219, v219
	v_cvt_pk_bf16_f32 v212, v212, v213
	v_cvt_pk_bf16_f32 v213, v214, v215
	v_cvt_pk_bf16_f32 v214, v216, v217
	v_cvt_pk_bf16_f32 v215, v218, v219
	global_store_dwordx4 v[150:151], v[212:215], off offset:256 nt
	s_mov_b64 s[4:5], 0
; __device__ __forceinline__ f32x4 sig4(f32x4 v) { return (f32x4){sigmoidf_(v[0]), sigmoidf_(v[1]), sigmoidf_(v[2]), sigmoidf_(v[3])}; }
; __device__ __forceinline__ f32x4 silu4(f32x4 v) { return v * sig4(v); }
; __device__ __forceinline__ u32x4 pack8(f32x4 a, f32x4 b) { u32x4 w; w.x = cvt_pk_bf16(a[0], a[1]); w.y = cvt_pk_bf16(a[2], a[3]); w.z = cvt_pk_bf16(b[0], b[1]); w.w = cvt_pk_bf16(b[2], b[3]); return w; }
;     template <int MODE> __device__ __forceinline__ void body(AccRef acc, int row0, size_t hc, int ld) const {
; #pragma unroll
;         for (int ai = 0; ai < 2; ++ai)
; #pragma unroll
;             for (int m = 0; m < 4; ++m) { bf16_t* rowp = H + (size_t)(row0 + ai * 128 + m * 16) * ld + hc;
; #pragma unroll
;                 for (int bj = 0; bj < 2; ++bj) { f32x4 v0 = acc[ai][bj][m][0], v1 = acc[ai][bj][m][1];
;                     if (MODE == 1) { v0 = silu4(v0); v1 = silu4(v1); }
;                     if (MODE == 2) { v0 = sig4(v0); v1 = sig4(v1); }
;                     *(u32x4*)(rowp + bj * 128) = pack8(v0, v1); } }
.LBB0_234:
	s_andn2_b64 vcc, exec, s[4:5]
	s_cbranch_vccnz .LBB0_236
	v_exp_f32_e32 v150, v211
	v_exp_f32_e32 v151, v210
	v_exp_f32_e32 v209, v209
	v_exp_f32_e32 v210, v208
	v_add_f32_e32 v150, 1.0, v150
	v_add_f32_e32 v151, 1.0, v151
	v_add_f32_e32 v208, 1.0, v209
	v_add_f32_e32 v209, 1.0, v210
	v_rcp_f32_e32 v150, v150
	v_rcp_f32_e32 v208, v208
	v_rcp_f32_e32 v209, v209
	v_rcp_f32_e32 v151, v151
	v_pk_mul_f32 v[148:149], v[122:123], v[148:149]
	v_pk_mul_f32 v[146:147], v[120:121], v[146:147]
	v_pk_mul_f32 v[208:209], v[114:115], v[208:209]
	v_pk_mul_f32 v[150:151], v[112:113], v[150:151]
	v_cvt_pk_bf16_f32 v146, v146, v147
	v_cvt_pk_bf16_f32 v147, v148, v149
	v_mul_f32_e32 v148, 0xbfb8aa3b, v124
	v_exp_f32_e32 v210, v148
	v_cvt_pk_bf16_f32 v148, v150, v151
	v_cvt_pk_bf16_f32 v149, v208, v209
	global_store_dwordx4 v[144:145], v[146:149], off nt
	v_mul_f32_e32 v150, 0xbfb8aa3b, v116
	v_mul_f32_e32 v151, 0xbfb8aa3b, v117
	v_mul_f32_e32 v147, 0xbfb8aa3b, v125
	v_mul_f32_e32 v148, 0xbfb8aa3b, v126
	v_mul_f32_e32 v149, 0xbfb8aa3b, v127
	v_mul_f32_e32 v208, 0xbfb8aa3b, v118
	v_mul_f32_e32 v209, 0xbfb8aa3b, v119
	v_exp_f32_e32 v147, v147
	v_exp_f32_e32 v148, v148
	v_exp_f32_e32 v149, v149
	v_exp_f32_e32 v150, v150
	v_exp_f32_e32 v151, v151
	v_exp_f32_e32 v208, v208
	v_exp_f32_e32 v209, v209
	v_add_f32_e32 v146, 1.0, v210
	v_add_f32_e32 v147, 1.0, v147
	v_add_f32_e32 v148, 1.0, v148
	v_add_f32_e32 v149, 1.0, v149
	v_add_f32_e32 v150, 1.0, v150
	v_add_f32_e32 v151, 1.0, v151
	v_add_f32_e32 v208, 1.0, v208
	v_add_f32_e32 v209, 1.0, v209
	v_rcp_f32_e32 v146, v146
	v_rcp_f32_e32 v147, v147
	v_rcp_f32_e32 v148, v148
	v_rcp_f32_e32 v149, v149
	v_rcp_f32_e32 v150, v150
	v_rcp_f32_e32 v208, v208
	v_rcp_f32_e32 v209, v209
	v_rcp_f32_e32 v151, v151
	v_pk_mul_f32 v[148:149], v[126:127], v[148:149]
	v_pk_mul_f32 v[146:147], v[124:125], v[146:147]
	v_pk_mul_f32 v[208:209], v[118:119], v[208:209]
	v_pk_mul_f32 v[150:151], v[116:117], v[150:151]
	v_cvt_pk_bf16_f32 v146, v146, v147
	v_cvt_pk_bf16_f32 v147, v148, v149
	v_cvt_pk_bf16_f32 v148, v150, v151
	v_cvt_pk_bf16_f32 v149, v208, v209
	global_store_dwordx4 v[144:145], v[146:149], off offset:256 nt
	v_exp_f32_e32 v150, v207
	v_exp_f32_e32 v203, v203
	v_or_b32_e32 v146, 16, v155
	v_mul_lo_u32 v148, s19, v146
	v_mad_u64_u32 v[146:147], s[4:5], s18, v146, 0
	v_add3_u32 v147, v147, v156, v148
	v_lshl_add_u64 v[148:149], v[146:147], 1, s[8:9]
	v_lshlrev_b64 v[146:147], 1, v[142:143]
	v_lshl_add_u64 v[208:209], v[148:149], 0, v[146:147]
	v_exp_f32_e32 v149, v206
	v_add_f32_e32 v148, 1.0, v150
	v_exp_f32_e32 v150, v205
	v_exp_f32_e32 v151, v204
	v_add_f32_e32 v203, 1.0, v203
	v_exp_f32_e32 v204, v202
	v_exp_f32_e32 v201, v201
	v_rcp_f32_e32 v202, v203
	v_exp_f32_e32 v203, v200
	v_add_f32_e32 v149, 1.0, v149
	v_add_f32_e32 v150, 1.0, v150
	v_add_f32_e32 v151, 1.0, v151
	v_rcp_f32_e32 v148, v148
	v_rcp_f32_e32 v149, v149
	v_rcp_f32_e32 v150, v150
	v_rcp_f32_e32 v151, v151
	v_add_f32_e32 v204, 1.0, v204
	v_add_f32_e32 v200, 1.0, v201
	v_add_f32_e32 v201, 1.0, v203
	v_rcp_f32_e32 v200, v200
	v_rcp_f32_e32 v201, v201
	v_rcp_f32_e32 v203, v204
	v_pk_mul_f32 v[150:151], v[106:107], v[150:151]
	v_pk_mul_f32 v[148:149], v[104:105], v[148:149]
	v_pk_mul_f32 v[200:201], v[98:99], v[200:201]
	v_pk_mul_f32 v[202:203], v[96:97], v[202:203]
	v_cvt_pk_bf16_f32 v148, v148, v149
	v_cvt_pk_bf16_f32 v149, v150, v151
	v_mul_f32_e32 v150, 0xbfb8aa3b, v108
	v_exp_f32_e32 v204, v150
	v_cvt_pk_bf16_f32 v150, v202, v203
	v_cvt_pk_bf16_f32 v151, v200, v201
	global_store_dwordx4 v[208:209], v[148:151], off nt
	v_mul_f32_e32 v200, 0xbfb8aa3b, v100
	v_mul_f32_e32 v201, 0xbfb8aa3b, v101
	v_mul_f32_e32 v149, 0xbfb8aa3b, v109
	v_mul_f32_e32 v150, 0xbfb8aa3b, v110
	v_mul_f32_e32 v151, 0xbfb8aa3b, v111
	v_mul_f32_e32 v202, 0xbfb8aa3b, v102
	v_mul_f32_e32 v203, 0xbfb8aa3b, v103
	v_exp_f32_e32 v149, v149
	v_exp_f32_e32 v150, v150
	v_exp_f32_e32 v151, v151
	v_exp_f32_e32 v200, v200
	v_exp_f32_e32 v201, v201
	v_exp_f32_e32 v202, v202
	v_exp_f32_e32 v203, v203
	v_add_f32_e32 v148, 1.0, v204
	v_add_f32_e32 v149, 1.0, v149
	v_add_f32_e32 v150, 1.0, v150
	v_add_f32_e32 v151, 1.0, v151
	v_add_f32_e32 v200, 1.0, v200
	v_add_f32_e32 v201, 1.0, v201
	v_add_f32_e32 v202, 1.0, v202
	v_add_f32_e32 v203, 1.0, v203
	v_rcp_f32_e32 v148, v148
	v_rcp_f32_e32 v149, v149
	v_rcp_f32_e32 v150, v150
	v_rcp_f32_e32 v151, v151
	v_rcp_f32_e32 v200, v200
	v_rcp_f32_e32 v202, v202
	v_rcp_f32_e32 v203, v203
	v_rcp_f32_e32 v201, v201
	v_pk_mul_f32 v[150:151], v[110:111], v[150:151]
	v_pk_mul_f32 v[148:149], v[108:109], v[148:149]
	v_pk_mul_f32 v[202:203], v[102:103], v[202:203]
	v_pk_mul_f32 v[200:201], v[100:101], v[200:201]
	v_cvt_pk_bf16_f32 v148, v148, v149
	v_cvt_pk_bf16_f32 v149, v150, v151
	v_cvt_pk_bf16_f32 v150, v200, v201
	v_cvt_pk_bf16_f32 v151, v202, v203
	global_store_dwordx4 v[208:209], v[148:151], off offset:256 nt
	v_exp_f32_e32 v193, v193
	v_exp_f32_e32 v187, v187
	v_or_b32_e32 v148, 32, v155
	v_mul_lo_u32 v150, s19, v148
	v_mad_u64_u32 v[148:149], s[4:5], s18, v148, 0
	v_add3_u32 v149, v149, v156, v150
	v_exp_f32_e32 v150, v199
	v_lshl_add_u64 v[148:149], v[148:149], 1, s[8:9]
	v_lshl_add_u64 v[200:201], v[148:149], 0, v[146:147]
	v_exp_f32_e32 v149, v198
	v_add_f32_e32 v148, 1.0, v150
	v_exp_f32_e32 v150, v197
	v_exp_f32_e32 v151, v196
	v_add_f32_e32 v193, 1.0, v193
	v_exp_f32_e32 v196, v192
	v_rcp_f32_e32 v192, v193
	v_exp_f32_e32 v193, v186
	v_add_f32_e32 v149, 1.0, v149
	v_add_f32_e32 v150, 1.0, v150
	v_add_f32_e32 v151, 1.0, v151
	v_rcp_f32_e32 v148, v148
	v_rcp_f32_e32 v149, v149
	v_rcp_f32_e32 v150, v150
	v_rcp_f32_e32 v151, v151
	v_add_f32_e32 v196, 1.0, v196
; __device__ __forceinline__ f32x4 sig4(f32x4 v) { return (f32x4){sigmoidf_(v[0]), sigmoidf_(v[1]), sigmoidf_(v[2]), sigmoidf_(v[3])}; }
; __device__ __forceinline__ f32x4 silu4(f32x4 v) { return v * sig4(v); }
; __device__ __forceinline__ u32x4 pack8(f32x4 a, f32x4 b) { u32x4 w; w.x = cvt_pk_bf16(a[0], a[1]); w.y = cvt_pk_bf16(a[2], a[3]); w.z = cvt_pk_bf16(b[0], b[1]); w.w = cvt_pk_bf16(b[2], b[3]); return w; }
;     template <int MODE> __device__ __forceinline__ void body(AccRef acc, int row0, size_t hc, int ld) const {
; #pragma unroll
;         for (int ai = 0; ai < 2; ++ai)
; #pragma unroll
;             for (int m = 0; m < 4; ++m) { bf16_t* rowp = H + (size_t)(row0 + ai * 128 + m * 16) * ld + hc;
; #pragma unroll
;                 for (int bj = 0; bj < 2; ++bj) { f32x4 v0 = acc[ai][bj][m][0], v1 = acc[ai][bj][m][1];
;                     if (MODE == 1) { v0 = silu4(v0); v1 = silu4(v1); }
;                     if (MODE == 2) { v0 = sig4(v0); v1 = sig4(v1); }
;                     *(u32x4*)(rowp + bj * 128) = pack8(v0, v1); } }
	v_add_f32_e32 v186, 1.0, v187
	v_add_f32_e32 v187, 1.0, v193
	v_rcp_f32_e32 v186, v186
	v_rcp_f32_e32 v187, v187
	v_rcp_f32_e32 v193, v196
	v_pk_mul_f32 v[150:151], v[90:91], v[150:151]
	v_pk_mul_f32 v[148:149], v[88:89], v[148:149]
	v_pk_mul_f32 v[186:187], v[82:83], v[186:187]
	v_pk_mul_f32 v[192:193], v[80:81], v[192:193]
	v_cvt_pk_bf16_f32 v148, v148, v149
	v_cvt_pk_bf16_f32 v149, v150, v151
	v_mul_f32_e32 v150, 0xbfb8aa3b, v92
	v_exp_f32_e32 v196, v150
	v_cvt_pk_bf16_f32 v150, v192, v193
	v_cvt_pk_bf16_f32 v151, v186, v187
	global_store_dwordx4 v[200:201], v[148:151], off nt
	v_mul_f32_e32 v186, 0xbfb8aa3b, v84
	v_mul_f32_e32 v187, 0xbfb8aa3b, v85
	v_mul_f32_e32 v149, 0xbfb8aa3b, v93
	v_mul_f32_e32 v150, 0xbfb8aa3b, v94
	v_mul_f32_e32 v151, 0xbfb8aa3b, v95
	v_mul_f32_e32 v192, 0xbfb8aa3b, v86
	v_mul_f32_e32 v193, 0xbfb8aa3b, v87
	v_exp_f32_e32 v149, v149
	v_exp_f32_e32 v150, v150
	v_exp_f32_e32 v151, v151
	v_exp_f32_e32 v186, v186
	v_exp_f32_e32 v187, v187
	v_exp_f32_e32 v192, v192
	v_exp_f32_e32 v193, v193
	v_add_f32_e32 v148, 1.0, v196
	v_add_f32_e32 v149, 1.0, v149
	v_add_f32_e32 v150, 1.0, v150
	v_add_f32_e32 v151, 1.0, v151
	v_add_f32_e32 v186, 1.0, v186
	v_add_f32_e32 v187, 1.0, v187
	v_add_f32_e32 v192, 1.0, v192
	v_add_f32_e32 v193, 1.0, v193
	v_rcp_f32_e32 v148, v148
	v_rcp_f32_e32 v149, v149
	v_rcp_f32_e32 v150, v150
	v_rcp_f32_e32 v151, v151
	v_rcp_f32_e32 v186, v186
	v_rcp_f32_e32 v192, v192
	v_rcp_f32_e32 v193, v193
	v_rcp_f32_e32 v187, v187
	v_pk_mul_f32 v[150:151], v[94:95], v[150:151]
	v_pk_mul_f32 v[148:149], v[92:93], v[148:149]
	v_pk_mul_f32 v[192:193], v[86:87], v[192:193]
	v_pk_mul_f32 v[186:187], v[84:85], v[186:187]
	v_cvt_pk_bf16_f32 v148, v148, v149
	v_cvt_pk_bf16_f32 v149, v150, v151
	v_cvt_pk_bf16_f32 v150, v186, v187
	v_cvt_pk_bf16_f32 v151, v192, v193
	global_store_dwordx4 v[200:201], v[148:151], off offset:256 nt
	v_exp_f32_e32 v179, v179
	v_exp_f32_e32 v177, v177
	v_or_b32_e32 v148, 48, v155
	v_mul_lo_u32 v150, s19, v148
	v_mad_u64_u32 v[148:149], s[4:5], s18, v148, 0
	v_add3_u32 v149, v149, v156, v150
	v_exp_f32_e32 v150, v183
	v_lshl_add_u64 v[148:149], v[148:149], 1, s[8:9]
	v_lshl_add_u64 v[186:187], v[148:149], 0, v[146:147]
	v_exp_f32_e32 v149, v182
	v_add_f32_e32 v148, 1.0, v150
	v_exp_f32_e32 v150, v181
	v_exp_f32_e32 v151, v180
	v_add_f32_e32 v179, 1.0, v179
	v_exp_f32_e32 v180, v178
	v_rcp_f32_e32 v178, v179
	v_exp_f32_e32 v179, v176
	v_add_f32_e32 v149, 1.0, v149
	v_add_f32_e32 v150, 1.0, v150
	v_add_f32_e32 v151, 1.0, v151
	v_rcp_f32_e32 v148, v148
	v_rcp_f32_e32 v149, v149
	v_rcp_f32_e32 v150, v150
	v_rcp_f32_e32 v151, v151
	v_add_f32_e32 v180, 1.0, v180
	v_add_f32_e32 v176, 1.0, v177
	v_add_f32_e32 v177, 1.0, v179
	v_rcp_f32_e32 v176, v176
	v_rcp_f32_e32 v177, v177
	v_rcp_f32_e32 v179, v180
	v_pk_mul_f32 v[150:151], v[74:75], v[150:151]
	v_pk_mul_f32 v[148:149], v[72:73], v[148:149]
	v_pk_mul_f32 v[176:177], v[66:67], v[176:177]
	v_pk_mul_f32 v[178:179], v[64:65], v[178:179]
	v_cvt_pk_bf16_f32 v148, v148, v149
	v_cvt_pk_bf16_f32 v149, v150, v151
	v_mul_f32_e32 v150, 0xbfb8aa3b, v76
	v_exp_f32_e32 v180, v150
	v_cvt_pk_bf16_f32 v150, v178, v179
	v_cvt_pk_bf16_f32 v151, v176, v177
	global_store_dwordx4 v[186:187], v[148:151], off nt
	v_mul_f32_e32 v176, 0xbfb8aa3b, v68
	v_mul_f32_e32 v177, 0xbfb8aa3b, v69
	v_mul_f32_e32 v149, 0xbfb8aa3b, v77
	v_mul_f32_e32 v150, 0xbfb8aa3b, v78
	v_mul_f32_e32 v151, 0xbfb8aa3b, v79
	v_mul_f32_e32 v178, 0xbfb8aa3b, v70
	v_mul_f32_e32 v179, 0xbfb8aa3b, v71
	v_exp_f32_e32 v149, v149
	v_exp_f32_e32 v150, v150
	v_exp_f32_e32 v151, v151
	v_exp_f32_e32 v176, v176
	v_exp_f32_e32 v177, v177
	v_exp_f32_e32 v178, v178
	v_exp_f32_e32 v179, v179
	v_add_f32_e32 v148, 1.0, v180
	v_add_f32_e32 v149, 1.0, v149
	v_add_f32_e32 v150, 1.0, v150
	v_add_f32_e32 v151, 1.0, v151
	v_add_f32_e32 v176, 1.0, v176
	v_add_f32_e32 v177, 1.0, v177
	v_add_f32_e32 v178, 1.0, v178
	v_add_f32_e32 v179, 1.0, v179
	v_rcp_f32_e32 v148, v148
	v_rcp_f32_e32 v149, v149
	v_rcp_f32_e32 v150, v150
	v_rcp_f32_e32 v151, v151
	v_rcp_f32_e32 v176, v176
	v_rcp_f32_e32 v178, v178
	v_rcp_f32_e32 v179, v179
	v_rcp_f32_e32 v177, v177
	v_pk_mul_f32 v[150:151], v[78:79], v[150:151]
	v_pk_mul_f32 v[148:149], v[76:77], v[148:149]
	v_pk_mul_f32 v[178:179], v[70:71], v[178:179]
	v_pk_mul_f32 v[176:177], v[68:69], v[176:177]
	v_cvt_pk_bf16_f32 v148, v148, v149
	v_cvt_pk_bf16_f32 v149, v150, v151
	v_cvt_pk_bf16_f32 v150, v176, v177
	v_cvt_pk_bf16_f32 v151, v178, v179
	global_store_dwordx4 v[186:187], v[148:151], off offset:256 nt
	v_exp_f32_e32 v171, v171
	v_exp_f32_e32 v169, v169
	v_add_u32_e32 v148, 0x80, v155
	v_ashrrev_i32_e32 v149, 31, v148
	v_mul_lo_u32 v150, s18, v149
	v_mul_lo_u32 v151, s19, v148
	v_mad_u64_u32 v[148:149], s[4:5], s18, v148, 0
	v_add3_u32 v149, v149, v150, v151
	v_exp_f32_e32 v150, v175
	v_lshl_add_u64 v[148:149], v[148:149], 1, s[8:9]
	v_lshl_add_u64 v[176:177], v[148:149], 0, v[146:147]
	v_exp_f32_e32 v149, v174
	v_add_f32_e32 v148, 1.0, v150
	v_exp_f32_e32 v150, v173
	v_exp_f32_e32 v151, v172
	v_add_f32_e32 v171, 1.0, v171
	v_exp_f32_e32 v172, v170
	v_rcp_f32_e32 v170, v171
	v_exp_f32_e32 v171, v168
	v_add_f32_e32 v149, 1.0, v149
	v_add_f32_e32 v150, 1.0, v150
	v_add_f32_e32 v151, 1.0, v151
	v_rcp_f32_e32 v148, v148
	v_rcp_f32_e32 v149, v149
	v_rcp_f32_e32 v150, v150
	v_rcp_f32_e32 v151, v151
	v_add_f32_e32 v172, 1.0, v172
	v_add_f32_e32 v168, 1.0, v169
	v_add_f32_e32 v169, 1.0, v171
	v_rcp_f32_e32 v168, v168
	v_rcp_f32_e32 v169, v169
	v_rcp_f32_e32 v171, v172
	v_pk_mul_f32 v[150:151], v[58:59], v[150:151]
	v_pk_mul_f32 v[148:149], v[56:57], v[148:149]
	v_pk_mul_f32 v[168:169], v[50:51], v[168:169]
; __device__ __forceinline__ f32x4 sig4(f32x4 v) { return (f32x4){sigmoidf_(v[0]), sigmoidf_(v[1]), sigmoidf_(v[2]), sigmoidf_(v[3])}; }
; __device__ __forceinline__ f32x4 silu4(f32x4 v) { return v * sig4(v); }
; __device__ __forceinline__ u32x4 pack8(f32x4 a, f32x4 b) { u32x4 w; w.x = cvt_pk_bf16(a[0], a[1]); w.y = cvt_pk_bf16(a[2], a[3]); w.z = cvt_pk_bf16(b[0], b[1]); w.w = cvt_pk_bf16(b[2], b[3]); return w; }
;     template <int MODE> __device__ __forceinline__ void body(AccRef acc, int row0, size_t hc, int ld) const {
; #pragma unroll
;         for (int ai = 0; ai < 2; ++ai)
; #pragma unroll
;             for (int m = 0; m < 4; ++m) { bf16_t* rowp = H + (size_t)(row0 + ai * 128 + m * 16) * ld + hc;
; #pragma unroll
;                 for (int bj = 0; bj < 2; ++bj) { f32x4 v0 = acc[ai][bj][m][0], v1 = acc[ai][bj][m][1];
;                     if (MODE == 1) { v0 = silu4(v0); v1 = silu4(v1); }
;                     if (MODE == 2) { v0 = sig4(v0); v1 = sig4(v1); }
;                     *(u32x4*)(rowp + bj * 128) = pack8(v0, v1); } }
	v_pk_mul_f32 v[170:171], v[48:49], v[170:171]
	v_cvt_pk_bf16_f32 v148, v148, v149
	v_cvt_pk_bf16_f32 v149, v150, v151
	v_mul_f32_e32 v150, 0xbfb8aa3b, v60
	v_exp_f32_e32 v172, v150
	v_cvt_pk_bf16_f32 v150, v170, v171
	v_cvt_pk_bf16_f32 v151, v168, v169
	global_store_dwordx4 v[176:177], v[148:151], off nt
	v_mul_f32_e32 v168, 0xbfb8aa3b, v52
	v_mul_f32_e32 v169, 0xbfb8aa3b, v53
	v_mul_f32_e32 v149, 0xbfb8aa3b, v61
	v_mul_f32_e32 v150, 0xbfb8aa3b, v62
	v_mul_f32_e32 v151, 0xbfb8aa3b, v63
	v_mul_f32_e32 v170, 0xbfb8aa3b, v54
	v_mul_f32_e32 v171, 0xbfb8aa3b, v55
	v_exp_f32_e32 v149, v149
	v_exp_f32_e32 v150, v150
	v_exp_f32_e32 v151, v151
	v_exp_f32_e32 v168, v168
	v_exp_f32_e32 v169, v169
	v_exp_f32_e32 v170, v170
	v_exp_f32_e32 v171, v171
	v_add_f32_e32 v148, 1.0, v172
	v_add_f32_e32 v149, 1.0, v149
	v_add_f32_e32 v150, 1.0, v150
	v_add_f32_e32 v151, 1.0, v151
	v_add_f32_e32 v168, 1.0, v168
	v_add_f32_e32 v169, 1.0, v169
	v_add_f32_e32 v170, 1.0, v170
	v_add_f32_e32 v171, 1.0, v171
	v_rcp_f32_e32 v148, v148
	v_rcp_f32_e32 v149, v149
	v_rcp_f32_e32 v150, v150
	v_rcp_f32_e32 v151, v151
	v_rcp_f32_e32 v168, v168
	v_rcp_f32_e32 v170, v170
	v_rcp_f32_e32 v171, v171
	v_rcp_f32_e32 v169, v169
	v_pk_mul_f32 v[150:151], v[62:63], v[150:151]
	v_pk_mul_f32 v[148:149], v[60:61], v[148:149]
	v_pk_mul_f32 v[170:171], v[54:55], v[170:171]
	v_pk_mul_f32 v[168:169], v[52:53], v[168:169]
	v_cvt_pk_bf16_f32 v148, v148, v149
	v_cvt_pk_bf16_f32 v149, v150, v151
	v_cvt_pk_bf16_f32 v150, v168, v169
	v_cvt_pk_bf16_f32 v151, v170, v171
	global_store_dwordx4 v[176:177], v[148:151], off offset:256 nt
	v_exp_f32_e32 v163, v163
	v_exp_f32_e32 v161, v161
	v_add_u32_e32 v148, 0x90, v155
	v_ashrrev_i32_e32 v149, 31, v148
	v_mul_lo_u32 v150, s18, v149
	v_mul_lo_u32 v151, s19, v148
	v_mad_u64_u32 v[148:149], s[4:5], s18, v148, 0
	v_add3_u32 v149, v149, v150, v151
	v_exp_f32_e32 v150, v167
	v_lshl_add_u64 v[148:149], v[148:149], 1, s[8:9]
	v_lshl_add_u64 v[168:169], v[148:149], 0, v[146:147]
	v_exp_f32_e32 v149, v166
	v_add_f32_e32 v148, 1.0, v150
	v_exp_f32_e32 v150, v165
	v_exp_f32_e32 v151, v164
	v_add_f32_e32 v163, 1.0, v163
	v_exp_f32_e32 v164, v162
	v_rcp_f32_e32 v162, v163
	v_exp_f32_e32 v163, v160
	v_add_f32_e32 v149, 1.0, v149
	v_add_f32_e32 v150, 1.0, v150
	v_add_f32_e32 v151, 1.0, v151
	v_rcp_f32_e32 v148, v148
	v_rcp_f32_e32 v149, v149
	v_rcp_f32_e32 v150, v150
	v_rcp_f32_e32 v151, v151
	v_add_f32_e32 v164, 1.0, v164
	v_add_f32_e32 v160, 1.0, v161
	v_add_f32_e32 v161, 1.0, v163
	v_rcp_f32_e32 v160, v160
	v_rcp_f32_e32 v161, v161
	v_rcp_f32_e32 v163, v164
	v_pk_mul_f32 v[150:151], v[42:43], v[150:151]
	v_pk_mul_f32 v[148:149], v[40:41], v[148:149]
	v_pk_mul_f32 v[160:161], v[34:35], v[160:161]
	v_pk_mul_f32 v[162:163], v[32:33], v[162:163]
	v_cvt_pk_bf16_f32 v148, v148, v149
	v_cvt_pk_bf16_f32 v149, v150, v151
	v_mul_f32_e32 v150, 0xbfb8aa3b, v44
	v_exp_f32_e32 v164, v150
	v_cvt_pk_bf16_f32 v150, v162, v163
	v_cvt_pk_bf16_f32 v151, v160, v161
	global_store_dwordx4 v[168:169], v[148:151], off nt
	v_mul_f32_e32 v160, 0xbfb8aa3b, v36
	v_mul_f32_e32 v161, 0xbfb8aa3b, v37
	v_mul_f32_e32 v149, 0xbfb8aa3b, v45
	v_mul_f32_e32 v150, 0xbfb8aa3b, v46
	v_mul_f32_e32 v151, 0xbfb8aa3b, v47
	v_mul_f32_e32 v162, 0xbfb8aa3b, v38
	v_mul_f32_e32 v163, 0xbfb8aa3b, v39
	v_exp_f32_e32 v149, v149
	v_exp_f32_e32 v150, v150
	v_exp_f32_e32 v151, v151
	v_exp_f32_e32 v160, v160
	v_exp_f32_e32 v161, v161
	v_exp_f32_e32 v162, v162
	v_exp_f32_e32 v163, v163
	v_add_f32_e32 v148, 1.0, v164
	v_add_f32_e32 v149, 1.0, v149
	v_add_f32_e32 v150, 1.0, v150
	v_add_f32_e32 v151, 1.0, v151
	v_add_f32_e32 v160, 1.0, v160
	v_add_f32_e32 v161, 1.0, v161
	v_add_f32_e32 v162, 1.0, v162
	v_add_f32_e32 v163, 1.0, v163
	v_rcp_f32_e32 v148, v148
	v_rcp_f32_e32 v149, v149
	v_rcp_f32_e32 v150, v150
	v_rcp_f32_e32 v151, v151
	v_rcp_f32_e32 v160, v160
	v_rcp_f32_e32 v162, v162
	v_rcp_f32_e32 v163, v163
	v_rcp_f32_e32 v161, v161
	v_pk_mul_f32 v[150:151], v[46:47], v[150:151]
	v_pk_mul_f32 v[148:149], v[44:45], v[148:149]
	v_pk_mul_f32 v[162:163], v[38:39], v[162:163]
	v_pk_mul_f32 v[160:161], v[36:37], v[160:161]
	v_cvt_pk_bf16_f32 v148, v148, v149
	v_cvt_pk_bf16_f32 v149, v150, v151
	v_cvt_pk_bf16_f32 v150, v160, v161
	v_cvt_pk_bf16_f32 v151, v162, v163
	global_store_dwordx4 v[168:169], v[148:151], off offset:256 nt
	v_mul_f32_e32 v162, 0xbfb8aa3b, v19
	v_exp_f32_e32 v163, v162
	v_add_u32_e32 v148, 0xa0, v155
	v_ashrrev_i32_e32 v149, 31, v148
	v_mul_lo_u32 v150, s18, v149
	v_mul_lo_u32 v151, s19, v148
	v_mad_u64_u32 v[148:149], s[4:5], s18, v148, 0
	v_add3_u32 v149, v149, v150, v151
	v_exp_f32_e32 v150, v159
	v_lshl_add_u64 v[148:149], v[148:149], 1, s[8:9]
	v_lshl_add_u64 v[160:161], v[148:149], 0, v[146:147]
	v_mul_f32_e32 v151, 0xbfb8aa3b, v27
	v_add_f32_e32 v148, 1.0, v150
	v_exp_f32_e32 v150, v157
	v_mul_f32_e32 v157, 0xbfb8aa3b, v16
	v_exp_f32_e32 v157, v157
	v_exp_f32_e32 v149, v158
	v_exp_f32_e32 v151, v151
	v_mul_f32_e32 v159, 0xbfb8aa3b, v18
	v_add_f32_e32 v157, 1.0, v157
	v_rcp_f32_e32 v158, v157
	v_mul_f32_e32 v157, 0xbfb8aa3b, v17
	v_exp_f32_e32 v159, v159
	v_add_f32_e32 v149, 1.0, v149
; __device__ __forceinline__ f32x4 sig4(f32x4 v) { return (f32x4){sigmoidf_(v[0]), sigmoidf_(v[1]), sigmoidf_(v[2]), sigmoidf_(v[3])}; }
; __device__ __forceinline__ f32x4 silu4(f32x4 v) { return v * sig4(v); }
; __device__ __forceinline__ u32x4 pack8(f32x4 a, f32x4 b) { u32x4 w; w.x = cvt_pk_bf16(a[0], a[1]); w.y = cvt_pk_bf16(a[2], a[3]); w.z = cvt_pk_bf16(b[0], b[1]); w.w = cvt_pk_bf16(b[2], b[3]); return w; }
;     template <int MODE> __device__ __forceinline__ void body(AccRef acc, int row0, size_t hc, int ld) const {
; #pragma unroll
;         for (int ai = 0; ai < 2; ++ai)
; #pragma unroll
;             for (int m = 0; m < 4; ++m) { bf16_t* rowp = H + (size_t)(row0 + ai * 128 + m * 16) * ld + hc;
; #pragma unroll
;                 for (int bj = 0; bj < 2; ++bj) { f32x4 v0 = acc[ai][bj][m][0], v1 = acc[ai][bj][m][1];
;                     if (MODE == 1) { v0 = silu4(v0); v1 = silu4(v1); }
;                     if (MODE == 2) { v0 = sig4(v0); v1 = sig4(v1); }
;                     *(u32x4*)(rowp + bj * 128) = pack8(v0, v1); } }
	v_add_f32_e32 v150, 1.0, v150
	v_add_f32_e32 v151, 1.0, v151
	v_exp_f32_e32 v157, v157
	v_rcp_f32_e32 v148, v148
	v_rcp_f32_e32 v149, v149
	v_rcp_f32_e32 v150, v150
	v_rcp_f32_e32 v151, v151
	v_add_f32_e32 v159, 1.0, v159
	v_add_f32_e32 v157, 1.0, v157
	v_rcp_f32_e32 v162, v159
	v_add_f32_e32 v159, 1.0, v163
	v_rcp_f32_e32 v163, v159
	v_rcp_f32_e32 v159, v157
	v_pk_mul_f32 v[150:151], v[26:27], v[150:151]
	v_pk_mul_f32 v[148:149], v[24:25], v[148:149]
	v_pk_mul_f32 v[162:163], v[18:19], v[162:163]
	v_cvt_pk_bf16_f32 v148, v148, v149
	v_cvt_pk_bf16_f32 v149, v150, v151
	v_mul_f32_e32 v150, 0xbfb8aa3b, v28
	v_exp_f32_e32 v157, v150
	v_pk_mul_f32 v[158:159], v[16:17], v[158:159]
	v_cvt_pk_bf16_f32 v151, v162, v163
	v_cvt_pk_bf16_f32 v150, v158, v159
	global_store_dwordx4 v[160:161], v[148:151], off nt
	v_mul_f32_e32 v159, 0xbfb8aa3b, v22
	v_exp_f32_e32 v159, v159
	v_add_f32_e32 v148, 1.0, v157
	v_mul_f32_e32 v157, 0xbfb8aa3b, v20
	v_exp_f32_e32 v157, v157
	v_mul_f32_e32 v149, 0xbfb8aa3b, v29
	v_mul_f32_e32 v150, 0xbfb8aa3b, v30
	v_mul_f32_e32 v151, 0xbfb8aa3b, v31
	v_add_f32_e32 v157, 1.0, v157
	v_rcp_f32_e32 v158, v157
	v_mul_f32_e32 v157, 0xbfb8aa3b, v21
	v_mul_f32_e32 v162, 0xbfb8aa3b, v23
	v_exp_f32_e32 v149, v149
	v_exp_f32_e32 v150, v150
	v_exp_f32_e32 v151, v151
	v_exp_f32_e32 v157, v157
	v_exp_f32_e32 v163, v162
	v_add_f32_e32 v159, 1.0, v159
	v_add_f32_e32 v149, 1.0, v149
	v_add_f32_e32 v150, 1.0, v150
	v_add_f32_e32 v151, 1.0, v151
	v_add_f32_e32 v157, 1.0, v157
	v_rcp_f32_e32 v162, v159
	v_add_f32_e32 v159, 1.0, v163
	v_rcp_f32_e32 v148, v148
	v_rcp_f32_e32 v149, v149
	v_rcp_f32_e32 v150, v150
	v_rcp_f32_e32 v151, v151
	v_rcp_f32_e32 v163, v159
	v_rcp_f32_e32 v159, v157
	v_pk_mul_f32 v[148:149], v[28:29], v[148:149]
	v_pk_mul_f32 v[150:151], v[30:31], v[150:151]
	v_pk_mul_f32 v[162:163], v[22:23], v[162:163]
	v_pk_mul_f32 v[158:159], v[20:21], v[158:159]
	v_cvt_pk_bf16_f32 v148, v148, v149
	v_cvt_pk_bf16_f32 v149, v150, v151
	v_cvt_pk_bf16_f32 v150, v158, v159
	v_cvt_pk_bf16_f32 v151, v162, v163
	global_store_dwordx4 v[160:161], v[148:151], off offset:256 nt
	v_mul_f32_e32 v157, 0xbfb8aa3b, v4
	v_exp_f32_e32 v157, v157
	v_add_u32_e32 v148, 0xb0, v155
	v_ashrrev_i32_e32 v149, 31, v148
	v_mul_lo_u32 v150, s18, v149
	v_mul_lo_u32 v151, s19, v148
	v_mad_u64_u32 v[148:149], s[4:5], s18, v148, 0
	v_add3_u32 v149, v149, v150, v151
	v_lshl_add_u64 v[148:149], v[148:149], 1, s[8:9]
	v_lshl_add_u64 v[150:151], v[148:149], 0, v[146:147]
	v_add_f32_e32 v146, 1.0, v157
	v_mul_f32_e32 v157, 0xbfb8aa3b, v0
	v_exp_f32_e32 v157, v157
	v_mul_f32_e32 v147, 0xbfb8aa3b, v5
	v_mul_f32_e32 v148, 0xbfb8aa3b, v6
	v_mul_f32_e32 v149, 0xbfb8aa3b, v7
	v_exp_f32_e32 v147, v147
	v_exp_f32_e32 v148, v148
	v_exp_f32_e32 v149, v149
	v_add_f32_e32 v157, 1.0, v157
	v_mul_f32_e32 v159, 0xbfb8aa3b, v2
	v_rcp_f32_e32 v158, v157
	v_mul_f32_e32 v157, 0xbfb8aa3b, v1
	v_exp_f32_e32 v159, v159
	v_mul_f32_e32 v160, 0xbfb8aa3b, v3
	v_add_f32_e32 v147, 1.0, v147
	v_add_f32_e32 v148, 1.0, v148
	v_add_f32_e32 v149, 1.0, v149
	v_exp_f32_e32 v157, v157
	v_exp_f32_e32 v161, v160
	v_rcp_f32_e32 v146, v146
	v_rcp_f32_e32 v147, v147
	v_rcp_f32_e32 v148, v148
	v_rcp_f32_e32 v149, v149
	v_add_f32_e32 v159, 1.0, v159
	v_add_f32_e32 v157, 1.0, v157
	v_rcp_f32_e32 v160, v159
	v_add_f32_e32 v159, 1.0, v161
	v_rcp_f32_e32 v161, v159
	v_rcp_f32_e32 v159, v157
	v_pk_mul_f32 v[148:149], v[6:7], v[148:149]
	v_pk_mul_f32 v[146:147], v[4:5], v[146:147]
	v_pk_mul_f32 v[160:161], v[2:3], v[160:161]
	v_cvt_pk_bf16_f32 v146, v146, v147
	v_cvt_pk_bf16_f32 v147, v148, v149
	v_mul_f32_e32 v148, 0xbfb8aa3b, v12
	v_exp_f32_e32 v157, v148
	v_pk_mul_f32 v[158:159], v[0:1], v[158:159]
	v_cvt_pk_bf16_f32 v149, v160, v161
	v_cvt_pk_bf16_f32 v148, v158, v159
	global_store_dwordx4 v[150:151], v[146:149], off nt
	v_mul_f32_e32 v159, 0xbfb8aa3b, v10
	v_exp_f32_e32 v159, v159
	v_add_f32_e32 v146, 1.0, v157
	v_mul_f32_e32 v157, 0xbfb8aa3b, v8
	v_exp_f32_e32 v157, v157
	v_mul_f32_e32 v147, 0xbfb8aa3b, v13
	v_mul_f32_e32 v148, 0xbfb8aa3b, v14
	v_mul_f32_e32 v149, 0xbfb8aa3b, v15
	v_add_f32_e32 v157, 1.0, v157
	v_rcp_f32_e32 v158, v157
	v_mul_f32_e32 v157, 0xbfb8aa3b, v9
	v_mul_f32_e32 v160, 0xbfb8aa3b, v11
	v_exp_f32_e32 v147, v147
	v_exp_f32_e32 v148, v148
	v_exp_f32_e32 v149, v149
	v_exp_f32_e32 v157, v157
	v_exp_f32_e32 v161, v160
	v_add_f32_e32 v159, 1.0, v159
	v_add_f32_e32 v147, 1.0, v147
	v_add_f32_e32 v148, 1.0, v148
	v_add_f32_e32 v149, 1.0, v149
	v_add_f32_e32 v157, 1.0, v157
	v_rcp_f32_e32 v160, v159
	v_add_f32_e32 v159, 1.0, v161
	v_rcp_f32_e32 v146, v146
	v_rcp_f32_e32 v147, v147
	v_rcp_f32_e32 v148, v148
	v_rcp_f32_e32 v149, v149
	v_rcp_f32_e32 v161, v159
	v_rcp_f32_e32 v159, v157
	v_pk_mul_f32 v[146:147], v[12:13], v[146:147]
	v_pk_mul_f32 v[148:149], v[14:15], v[148:149]
	v_pk_mul_f32 v[160:161], v[10:11], v[160:161]
	v_pk_mul_f32 v[158:159], v[8:9], v[158:159]
	v_cvt_pk_bf16_f32 v146, v146, v147
	v_cvt_pk_bf16_f32 v147, v148, v149
	v_cvt_pk_bf16_f32 v148, v158, v159
	v_cvt_pk_bf16_f32 v149, v160, v161
	global_store_dwordx4 v[150:151], v[146:149], off offset:256 nt

; __device__ __forceinline__ f32x4 sig4(f32x4 v) { return (f32x4){sigmoidf_(v[0]), sigmoidf_(v[1]), sigmoidf_(v[2]), sigmoidf_(v[3])}; }
; __device__ __forceinline__ f32x4 silu4(f32x4 v) { return v * sig4(v); }
; __device__ __forceinline__ u32x4 pack8(f32x4 a, f32x4 b) { u32x4 w; w.x = cvt_pk_bf16(a[0], a[1]); w.y = cvt_pk_bf16(a[2], a[3]); w.z = cvt_pk_bf16(b[0], b[1]); w.w = cvt_pk_bf16(b[2], b[3]); return w; }
;     template <int MODE> __device__ __forceinline__ void body(AccRef acc, int row0, size_t hc, int ld) const {
; #pragma unroll
;         for (int ai = 0; ai < 2; ++ai)
; #pragma unroll
;             for (int m = 0; m < 4; ++m) { bf16_t* rowp = H + (size_t)(row0 + ai * 128 + m * 16) * ld + hc;
; #pragma unroll
;                 for (int bj = 0; bj < 2; ++bj) { f32x4 v0 = acc[ai][bj][m][0], v1 = acc[ai][bj][m][1];
;                     if (MODE == 1) { v0 = silu4(v0); v1 = silu4(v1); }
;                     if (MODE == 2) { v0 = sig4(v0); v1 = sig4(v1); }
;                     *(u32x4*)(rowp + bj * 128) = pack8(v0, v1); } }
.LBB0_237:
	s_andn2_b64 vcc, exec, s[4:5]
	s_cbranch_vccnz .LBB0_239
	v_cvt_pk_bf16_f32 v146, v120, v121
	v_cvt_pk_bf16_f32 v147, v122, v123
	v_cvt_pk_bf16_f32 v148, v112, v113
	v_cvt_pk_bf16_f32 v149, v114, v115
	global_store_dwordx4 v[144:145], v[146:149], off nt
	v_lshlrev_b64 v[150:151], 1, v[142:143]
	s_nop 0
	v_cvt_pk_bf16_f32 v146, v124, v125
	v_cvt_pk_bf16_f32 v147, v126, v127
	v_cvt_pk_bf16_f32 v148, v116, v117
	v_cvt_pk_bf16_f32 v149, v118, v119
	global_store_dwordx4 v[144:145], v[146:149], off offset:256 nt
	s_nop 1
	v_or_b32_e32 v146, 16, v155
	v_mul_lo_u32 v148, s19, v146
	v_mad_u64_u32 v[146:147], s[4:5], s18, v146, 0
	v_add3_u32 v147, v147, v156, v148
	v_lshl_add_u64 v[146:147], v[146:147], 1, s[8:9]
	v_lshl_add_u64 v[158:159], v[146:147], 0, v[150:151]
	v_cvt_pk_bf16_f32 v146, v104, v105
	v_cvt_pk_bf16_f32 v147, v106, v107
	v_cvt_pk_bf16_f32 v148, v96, v97
	v_cvt_pk_bf16_f32 v149, v98, v99
	global_store_dwordx4 v[158:159], v[146:149], off nt
	s_nop 1
	v_cvt_pk_bf16_f32 v146, v108, v109
	v_cvt_pk_bf16_f32 v147, v110, v111
	v_cvt_pk_bf16_f32 v148, v100, v101
	v_cvt_pk_bf16_f32 v149, v102, v103
	global_store_dwordx4 v[158:159], v[146:149], off offset:256 nt
	s_nop 1
	v_or_b32_e32 v146, 32, v155
	v_mul_lo_u32 v148, s19, v146
	v_mad_u64_u32 v[146:147], s[4:5], s18, v146, 0
	v_add3_u32 v147, v147, v156, v148
	v_lshl_add_u64 v[146:147], v[146:147], 1, s[8:9]
	v_lshl_add_u64 v[158:159], v[146:147], 0, v[150:151]
	v_cvt_pk_bf16_f32 v146, v88, v89
	v_cvt_pk_bf16_f32 v147, v90, v91
	v_cvt_pk_bf16_f32 v148, v80, v81
	v_cvt_pk_bf16_f32 v149, v82, v83
	global_store_dwordx4 v[158:159], v[146:149], off nt
	s_nop 1
	v_cvt_pk_bf16_f32 v146, v92, v93
	v_cvt_pk_bf16_f32 v147, v94, v95
	v_cvt_pk_bf16_f32 v148, v84, v85
	v_cvt_pk_bf16_f32 v149, v86, v87
	global_store_dwordx4 v[158:159], v[146:149], off offset:256 nt
	s_nop 1
	v_or_b32_e32 v146, 48, v155
	v_mul_lo_u32 v148, s19, v146
	v_mad_u64_u32 v[146:147], s[4:5], s18, v146, 0
	v_add3_u32 v147, v147, v156, v148
	v_lshl_add_u64 v[146:147], v[146:147], 1, s[8:9]
	v_lshl_add_u64 v[158:159], v[146:147], 0, v[150:151]
	v_cvt_pk_bf16_f32 v146, v72, v73
	v_cvt_pk_bf16_f32 v147, v74, v75
	v_cvt_pk_bf16_f32 v148, v64, v65
	v_cvt_pk_bf16_f32 v149, v66, v67
	global_store_dwordx4 v[158:159], v[146:149], off nt
	s_nop 1
	v_cvt_pk_bf16_f32 v146, v76, v77
	v_cvt_pk_bf16_f32 v147, v78, v79
	v_cvt_pk_bf16_f32 v148, v68, v69
	v_cvt_pk_bf16_f32 v149, v70, v71
	global_store_dwordx4 v[158:159], v[146:149], off offset:256 nt
	s_nop 1
	v_add_u32_e32 v146, 0x80, v155
	v_ashrrev_i32_e32 v147, 31, v146
	v_mul_lo_u32 v148, s18, v147
	v_mul_lo_u32 v149, s19, v146
	v_mad_u64_u32 v[146:147], s[4:5], s18, v146, 0
	v_add3_u32 v147, v147, v148, v149
	v_lshl_add_u64 v[146:147], v[146:147], 1, s[8:9]
	v_lshl_add_u64 v[158:159], v[146:147], 0, v[150:151]
	v_cvt_pk_bf16_f32 v146, v56, v57
	v_cvt_pk_bf16_f32 v147, v58, v59
	v_cvt_pk_bf16_f32 v148, v48, v49
	v_cvt_pk_bf16_f32 v149, v50, v51
	global_store_dwordx4 v[158:159], v[146:149], off nt
	s_nop 1
	v_cvt_pk_bf16_f32 v146, v60, v61
	v_cvt_pk_bf16_f32 v147, v62, v63
	v_cvt_pk_bf16_f32 v148, v52, v53
	v_cvt_pk_bf16_f32 v149, v54, v55
	global_store_dwordx4 v[158:159], v[146:149], off offset:256 nt
	s_nop 1
	v_add_u32_e32 v146, 0x90, v155
	v_ashrrev_i32_e32 v147, 31, v146
	v_mul_lo_u32 v148, s18, v147
	v_mul_lo_u32 v149, s19, v146
	v_mad_u64_u32 v[146:147], s[4:5], s18, v146, 0
	v_add3_u32 v147, v147, v148, v149
	v_lshl_add_u64 v[146:147], v[146:147], 1, s[8:9]
	v_lshl_add_u64 v[158:159], v[146:147], 0, v[150:151]
	v_cvt_pk_bf16_f32 v146, v40, v41
	v_cvt_pk_bf16_f32 v147, v42, v43
	v_cvt_pk_bf16_f32 v148, v32, v33
	v_cvt_pk_bf16_f32 v149, v34, v35
	global_store_dwordx4 v[158:159], v[146:149], off nt
	s_nop 1
	v_cvt_pk_bf16_f32 v146, v44, v45
	v_cvt_pk_bf16_f32 v147, v46, v47
	v_cvt_pk_bf16_f32 v148, v36, v37
	v_cvt_pk_bf16_f32 v149, v38, v39
	global_store_dwordx4 v[158:159], v[146:149], off offset:256 nt
	s_nop 1
	v_add_u32_e32 v146, 0xa0, v155
	v_ashrrev_i32_e32 v147, 31, v146
	v_mul_lo_u32 v148, s18, v147
	v_mul_lo_u32 v149, s19, v146
	v_mad_u64_u32 v[146:147], s[4:5], s18, v146, 0
	v_add3_u32 v147, v147, v148, v149
	v_lshl_add_u64 v[146:147], v[146:147], 1, s[8:9]
	v_lshl_add_u64 v[158:159], v[146:147], 0, v[150:151]
	v_cvt_pk_bf16_f32 v146, v24, v25
	v_cvt_pk_bf16_f32 v147, v26, v27
	v_cvt_pk_bf16_f32 v148, v16, v17
	v_cvt_pk_bf16_f32 v149, v18, v19
	global_store_dwordx4 v[158:159], v[146:149], off nt
	s_nop 1
	v_cvt_pk_bf16_f32 v146, v28, v29
	v_cvt_pk_bf16_f32 v147, v30, v31
	v_cvt_pk_bf16_f32 v148, v20, v21
	v_cvt_pk_bf16_f32 v149, v22, v23
	global_store_dwordx4 v[158:159], v[146:149], off offset:256 nt
	s_nop 1
	v_add_u32_e32 v146, 0xb0, v155
	v_ashrrev_i32_e32 v147, 31, v146
	v_mul_lo_u32 v148, s18, v147
	v_mul_lo_u32 v149, s19, v146
	v_mad_u64_u32 v[146:147], s[4:5], s18, v146, 0
	v_add3_u32 v147, v147, v148, v149
	v_lshl_add_u64 v[146:147], v[146:147], 1, s[8:9]
	v_lshl_add_u64 v[150:151], v[146:147], 0, v[150:151]
	v_cvt_pk_bf16_f32 v146, v4, v5
	v_cvt_pk_bf16_f32 v147, v6, v7
	v_cvt_pk_bf16_f32 v148, v0, v1
	v_cvt_pk_bf16_f32 v149, v2, v3
	global_store_dwordx4 v[150:151], v[146:149], off nt
	s_nop 1
	v_cvt_pk_bf16_f32 v146, v12, v13
	v_cvt_pk_bf16_f32 v147, v14, v15
	v_cvt_pk_bf16_f32 v148, v8, v9
	v_cvt_pk_bf16_f32 v149, v10, v11
	global_store_dwordx4 v[150:151], v[146:149], off offset:256 nt

; __device__ __forceinline__ f32x4 sig4(f32x4 v) { return (f32x4){sigmoidf_(v[0]), sigmoidf_(v[1]), sigmoidf_(v[2]), sigmoidf_(v[3])}; }
; __device__ __forceinline__ u32x4 pack8(f32x4 a, f32x4 b) { u32x4 w; w.x = cvt_pk_bf16(a[0], a[1]); w.y = cvt_pk_bf16(a[2], a[3]); w.z = cvt_pk_bf16(b[0], b[1]); w.w = cvt_pk_bf16(b[2], b[3]); return w; }
;     __device__ __forceinline__ void operator()(AccRef acc, const Unit& u, int wr, int wc, int fr, int fq) const {
;     ...
;         if (mode == 3) {
; #pragma unroll
;             for (int ai = 0; ai < 2; ++ai)
; #pragma unroll
;                 for (int m = 0; m < 4; ++m) { bf16_t* rowp = H + (size_t)(row0 + ai * 128 + m * 16) * ld + hc;
;                     const f32x4 a0 = acc[ai][0][m][0], a1 = acc[ai][0][m][1], g0 = acc[ai][1][m][0], g1 = acc[ai][1][m][1];
;                     *(u32x4*)rowp = pack8(a0 * sig4(g0), a1 * sig4(g1)); }
.LBB0_241:
	v_mul_f32_e32 v124, 0xbfb8aa3b, v124
	v_mul_f32_e32 v125, 0xbfb8aa3b, v125
	v_mul_f32_e32 v126, 0xbfb8aa3b, v126
	v_mul_f32_e32 v127, 0xbfb8aa3b, v127
	v_mul_f32_e32 v116, 0xbfb8aa3b, v116
	v_mul_f32_e32 v117, 0xbfb8aa3b, v117
	v_mul_f32_e32 v118, 0xbfb8aa3b, v118
	v_mul_f32_e32 v119, 0xbfb8aa3b, v119
	v_exp_f32_e32 v124, v124
	v_exp_f32_e32 v125, v125
	v_exp_f32_e32 v126, v126
	v_exp_f32_e32 v127, v127
	v_exp_f32_e32 v116, v116
	v_exp_f32_e32 v117, v117
	v_exp_f32_e32 v118, v118
	v_exp_f32_e32 v119, v119
	v_add_f32_e32 v124, 1.0, v124
	v_add_f32_e32 v125, 1.0, v125
	v_add_f32_e32 v126, 1.0, v126
	v_add_f32_e32 v127, 1.0, v127
	v_add_f32_e32 v116, 1.0, v116
	v_add_f32_e32 v117, 1.0, v117
	v_add_f32_e32 v118, 1.0, v118
	v_add_f32_e32 v119, 1.0, v119
	v_mul_f32_e32 v108, 0xbfb8aa3b, v108
	v_mul_f32_e32 v109, 0xbfb8aa3b, v109
	v_mul_f32_e32 v110, 0xbfb8aa3b, v110
	v_mul_f32_e32 v111, 0xbfb8aa3b, v111
	v_mul_f32_e32 v100, 0xbfb8aa3b, v100
	v_mul_f32_e32 v101, 0xbfb8aa3b, v101
	v_mul_f32_e32 v102, 0xbfb8aa3b, v102
	v_mul_f32_e32 v103, 0xbfb8aa3b, v103
	v_rcp_f32_e32 v124, v124
	v_rcp_f32_e32 v125, v125
	v_rcp_f32_e32 v126, v126
	v_rcp_f32_e32 v127, v127
	v_rcp_f32_e32 v116, v116
	v_rcp_f32_e32 v118, v118
	v_rcp_f32_e32 v119, v119
	v_rcp_f32_e32 v117, v117
	v_exp_f32_e32 v108, v108
	v_exp_f32_e32 v109, v109
	v_exp_f32_e32 v110, v110
	v_exp_f32_e32 v111, v111
	v_exp_f32_e32 v100, v100
	v_exp_f32_e32 v101, v101
	v_exp_f32_e32 v102, v102
	v_exp_f32_e32 v103, v103
	v_pk_mul_f32 v[122:123], v[122:123], v[126:127]
	v_pk_mul_f32 v[120:121], v[120:121], v[124:125]
	v_pk_mul_f32 v[118:119], v[114:115], v[118:119]
	v_pk_mul_f32 v[114:115], v[112:113], v[116:117]
	v_add_f32_e32 v108, 1.0, v108
	v_add_f32_e32 v109, 1.0, v109
	v_add_f32_e32 v110, 1.0, v110
	v_add_f32_e32 v111, 1.0, v111
	v_add_f32_e32 v100, 1.0, v100
	v_add_f32_e32 v101, 1.0, v101
	v_add_f32_e32 v102, 1.0, v102
	v_add_f32_e32 v103, 1.0, v103
	v_mul_f32_e32 v92, 0xbfb8aa3b, v92
	v_mul_f32_e32 v93, 0xbfb8aa3b, v93
	v_mul_f32_e32 v94, 0xbfb8aa3b, v94
	v_mul_f32_e32 v95, 0xbfb8aa3b, v95
	v_mul_f32_e32 v84, 0xbfb8aa3b, v84
	v_mul_f32_e32 v85, 0xbfb8aa3b, v85
	v_mul_f32_e32 v86, 0xbfb8aa3b, v86
	v_mul_f32_e32 v87, 0xbfb8aa3b, v87
	v_cvt_pk_bf16_f32 v112, v120, v121
	v_cvt_pk_bf16_f32 v113, v122, v123
	v_cvt_pk_bf16_f32 v114, v114, v115
	v_cvt_pk_bf16_f32 v115, v118, v119
	v_rcp_f32_e32 v108, v108
	v_rcp_f32_e32 v109, v109
	v_rcp_f32_e32 v110, v110
	v_rcp_f32_e32 v111, v111
	v_rcp_f32_e32 v100, v100
	v_rcp_f32_e32 v102, v102
	v_rcp_f32_e32 v103, v103
	v_rcp_f32_e32 v101, v101
	v_exp_f32_e32 v92, v92
	v_exp_f32_e32 v93, v93
	v_exp_f32_e32 v94, v94
	v_exp_f32_e32 v95, v95
	v_exp_f32_e32 v84, v84
	v_exp_f32_e32 v85, v85
	v_exp_f32_e32 v86, v86
	v_exp_f32_e32 v87, v87
	global_store_dwordx4 v[144:145], v[112:115], off nt
	v_pk_mul_f32 v[106:107], v[106:107], v[110:111]
	v_pk_mul_f32 v[104:105], v[104:105], v[108:109]
	v_or_b32_e32 v112, 16, v155
	v_mul_lo_u32 v114, s19, v112
	v_mad_u64_u32 v[112:113], s[4:5], s18, v112, 0
	v_add3_u32 v113, v113, v156, v114
	v_lshl_add_u64 v[114:115], v[112:113], 1, s[8:9]
	v_lshlrev_b64 v[112:113], 1, v[142:143]
	v_pk_mul_f32 v[102:103], v[98:99], v[102:103]
	v_pk_mul_f32 v[98:99], v[96:97], v[100:101]
	v_add_f32_e32 v92, 1.0, v92
	v_add_f32_e32 v93, 1.0, v93
	v_add_f32_e32 v94, 1.0, v94
	v_add_f32_e32 v95, 1.0, v95
	v_add_f32_e32 v84, 1.0, v84
	v_add_f32_e32 v85, 1.0, v85
	v_add_f32_e32 v86, 1.0, v86
	v_add_f32_e32 v87, 1.0, v87
	v_mul_f32_e32 v76, 0xbfb8aa3b, v76
	v_mul_f32_e32 v77, 0xbfb8aa3b, v77
	v_mul_f32_e32 v78, 0xbfb8aa3b, v78
	v_mul_f32_e32 v79, 0xbfb8aa3b, v79
	v_mul_f32_e32 v68, 0xbfb8aa3b, v68
	v_mul_f32_e32 v69, 0xbfb8aa3b, v69
	v_mul_f32_e32 v70, 0xbfb8aa3b, v70
	v_mul_f32_e32 v71, 0xbfb8aa3b, v71
	v_lshl_add_u64 v[114:115], v[114:115], 0, v[112:113]
	v_cvt_pk_bf16_f32 v96, v104, v105
	v_cvt_pk_bf16_f32 v97, v106, v107
	v_cvt_pk_bf16_f32 v98, v98, v99
	v_cvt_pk_bf16_f32 v99, v102, v103
	v_rcp_f32_e32 v92, v92
	v_rcp_f32_e32 v93, v93
	v_rcp_f32_e32 v94, v94
	v_rcp_f32_e32 v95, v95
	v_rcp_f32_e32 v84, v84
	v_rcp_f32_e32 v86, v86
	v_rcp_f32_e32 v87, v87
	v_rcp_f32_e32 v85, v85
	v_exp_f32_e32 v76, v76
	v_exp_f32_e32 v77, v77
	v_exp_f32_e32 v78, v78
	v_exp_f32_e32 v79, v79
	v_exp_f32_e32 v68, v68
	v_exp_f32_e32 v69, v69
	v_exp_f32_e32 v70, v70
	v_exp_f32_e32 v71, v71
	global_store_dwordx4 v[114:115], v[96:99], off nt
	v_pk_mul_f32 v[90:91], v[90:91], v[94:95]
	v_pk_mul_f32 v[88:89], v[88:89], v[92:93]
	v_or_b32_e32 v96, 32, v155
	v_mul_lo_u32 v98, s19, v96
	v_mad_u64_u32 v[96:97], s[4:5], s18, v96, 0
	v_add3_u32 v97, v97, v156, v98
	v_lshl_add_u64 v[96:97], v[96:97], 1, s[8:9]
	v_pk_mul_f32 v[86:87], v[82:83], v[86:87]
	v_pk_mul_f32 v[82:83], v[80:81], v[84:85]
	v_add_f32_e32 v76, 1.0, v76
	v_add_f32_e32 v77, 1.0, v77
	v_add_f32_e32 v78, 1.0, v78
	v_add_f32_e32 v79, 1.0, v79
	v_add_f32_e32 v68, 1.0, v68
	v_add_f32_e32 v69, 1.0, v69
	v_add_f32_e32 v70, 1.0, v70
	v_add_f32_e32 v71, 1.0, v71
	v_lshl_add_u64 v[96:97], v[96:97], 0, v[112:113]
	v_cvt_pk_bf16_f32 v80, v88, v89
	v_cvt_pk_bf16_f32 v81, v90, v91
	v_cvt_pk_bf16_f32 v82, v82, v83
	v_cvt_pk_bf16_f32 v83, v86, v87
	v_rcp_f32_e32 v76, v76
	v_rcp_f32_e32 v77, v77
	v_rcp_f32_e32 v78, v78
	v_rcp_f32_e32 v79, v79
	v_rcp_f32_e32 v68, v68
	v_rcp_f32_e32 v70, v70
	v_rcp_f32_e32 v71, v71
	v_rcp_f32_e32 v69, v69
	v_mul_f32_e32 v60, 0xbfb8aa3b, v60
	v_mul_f32_e32 v61, 0xbfb8aa3b, v61
	v_mul_f32_e32 v62, 0xbfb8aa3b, v62
	v_mul_f32_e32 v63, 0xbfb8aa3b, v63
	v_mul_f32_e32 v52, 0xbfb8aa3b, v52
	v_mul_f32_e32 v53, 0xbfb8aa3b, v53
	v_mul_f32_e32 v54, 0xbfb8aa3b, v54
	v_mul_f32_e32 v55, 0xbfb8aa3b, v55
; __device__ __forceinline__ f32x4 sig4(f32x4 v) { return (f32x4){sigmoidf_(v[0]), sigmoidf_(v[1]), sigmoidf_(v[2]), sigmoidf_(v[3])}; }
; __device__ __forceinline__ u32x4 pack8(f32x4 a, f32x4 b) { u32x4 w; w.x = cvt_pk_bf16(a[0], a[1]); w.y = cvt_pk_bf16(a[2], a[3]); w.z = cvt_pk_bf16(b[0], b[1]); w.w = cvt_pk_bf16(b[2], b[3]); return w; }
;     __device__ __forceinline__ void operator()(AccRef acc, const Unit& u, int wr, int wc, int fr, int fq) const {
;     ...
;         if (mode == 3) {
; #pragma unroll
;             for (int ai = 0; ai < 2; ++ai)
; #pragma unroll
;                 for (int m = 0; m < 4; ++m) { bf16_t* rowp = H + (size_t)(row0 + ai * 128 + m * 16) * ld + hc;
;                     const f32x4 a0 = acc[ai][0][m][0], a1 = acc[ai][0][m][1], g0 = acc[ai][1][m][0], g1 = acc[ai][1][m][1];
;                     *(u32x4*)rowp = pack8(a0 * sig4(g0), a1 * sig4(g1)); }
	global_store_dwordx4 v[96:97], v[80:83], off nt
	v_exp_f32_e32 v60, v60
	v_exp_f32_e32 v61, v61
	v_or_b32_e32 v80, 48, v155
	v_exp_f32_e32 v62, v62
	v_exp_f32_e32 v63, v63
	v_exp_f32_e32 v52, v52
	v_exp_f32_e32 v53, v53
	v_exp_f32_e32 v54, v54
	v_exp_f32_e32 v55, v55
	v_mul_lo_u32 v82, s19, v80
	v_mad_u64_u32 v[80:81], s[4:5], s18, v80, 0
	v_add3_u32 v81, v81, v156, v82
	v_lshl_add_u64 v[80:81], v[80:81], 1, s[8:9]
	v_pk_mul_f32 v[74:75], v[74:75], v[78:79]
	v_pk_mul_f32 v[72:73], v[72:73], v[76:77]
	v_pk_mul_f32 v[70:71], v[66:67], v[70:71]
	v_pk_mul_f32 v[66:67], v[64:65], v[68:69]
	v_lshl_add_u64 v[80:81], v[80:81], 0, v[112:113]
	v_cvt_pk_bf16_f32 v64, v72, v73
	v_cvt_pk_bf16_f32 v65, v74, v75
	v_cvt_pk_bf16_f32 v66, v66, v67
	v_cvt_pk_bf16_f32 v67, v70, v71
	v_add_f32_e32 v60, 1.0, v60
	v_add_f32_e32 v61, 1.0, v61
	v_add_f32_e32 v62, 1.0, v62
	v_add_f32_e32 v63, 1.0, v63
	v_add_f32_e32 v52, 1.0, v52
	v_add_f32_e32 v53, 1.0, v53
	v_add_f32_e32 v54, 1.0, v54
	v_add_f32_e32 v55, 1.0, v55
	global_store_dwordx4 v[80:81], v[64:67], off nt
	v_rcp_f32_e32 v60, v60
	v_rcp_f32_e32 v61, v61
	v_add_u32_e32 v64, 0x80, v155
	v_rcp_f32_e32 v62, v62
	v_rcp_f32_e32 v63, v63
	v_rcp_f32_e32 v52, v52
	v_rcp_f32_e32 v54, v54
	v_rcp_f32_e32 v55, v55
	v_rcp_f32_e32 v53, v53
	v_mul_f32_e32 v44, 0xbfb8aa3b, v44
	v_mul_f32_e32 v45, 0xbfb8aa3b, v45
	v_mul_f32_e32 v46, 0xbfb8aa3b, v46
	v_mul_f32_e32 v47, 0xbfb8aa3b, v47
	v_mul_f32_e32 v36, 0xbfb8aa3b, v36
	v_mul_f32_e32 v37, 0xbfb8aa3b, v37
	v_mul_f32_e32 v38, 0xbfb8aa3b, v38
	v_mul_f32_e32 v39, 0xbfb8aa3b, v39
	v_ashrrev_i32_e32 v65, 31, v64
	v_exp_f32_e32 v44, v44
	v_exp_f32_e32 v45, v45
	v_exp_f32_e32 v46, v46
	v_exp_f32_e32 v47, v47
	v_exp_f32_e32 v36, v36
	v_exp_f32_e32 v37, v37
	v_exp_f32_e32 v38, v38
	v_exp_f32_e32 v39, v39
	v_mul_lo_u32 v66, s18, v65
	v_mul_lo_u32 v67, s19, v64
	v_mad_u64_u32 v[64:65], s[4:5], s18, v64, 0
	v_add3_u32 v65, v65, v66, v67
	v_lshl_add_u64 v[64:65], v[64:65], 1, s[8:9]
	v_pk_mul_f32 v[58:59], v[58:59], v[62:63]
	v_pk_mul_f32 v[56:57], v[56:57], v[60:61]
	v_pk_mul_f32 v[54:55], v[50:51], v[54:55]
	v_pk_mul_f32 v[50:51], v[48:49], v[52:53]
	v_lshl_add_u64 v[64:65], v[64:65], 0, v[112:113]
	v_cvt_pk_bf16_f32 v48, v56, v57
	v_cvt_pk_bf16_f32 v49, v58, v59
	v_cvt_pk_bf16_f32 v50, v50, v51
	v_cvt_pk_bf16_f32 v51, v54, v55
	v_add_f32_e32 v44, 1.0, v44
	v_add_f32_e32 v45, 1.0, v45
	v_add_f32_e32 v46, 1.0, v46
	v_add_f32_e32 v47, 1.0, v47
	v_add_f32_e32 v36, 1.0, v36
	v_add_f32_e32 v37, 1.0, v37
	v_add_f32_e32 v38, 1.0, v38
	v_add_f32_e32 v39, 1.0, v39
	global_store_dwordx4 v[64:65], v[48:51], off nt
	v_rcp_f32_e32 v44, v44
	v_rcp_f32_e32 v45, v45
	v_add_u32_e32 v48, 0x90, v155
	v_rcp_f32_e32 v46, v46
	v_rcp_f32_e32 v47, v47
	v_rcp_f32_e32 v36, v36
	v_rcp_f32_e32 v38, v38
	v_rcp_f32_e32 v39, v39
	v_rcp_f32_e32 v37, v37
	v_mul_f32_e32 v28, 0xbfb8aa3b, v28
	v_mul_f32_e32 v29, 0xbfb8aa3b, v29
	v_mul_f32_e32 v30, 0xbfb8aa3b, v30
	v_mul_f32_e32 v31, 0xbfb8aa3b, v31
	v_mul_f32_e32 v20, 0xbfb8aa3b, v20
	v_mul_f32_e32 v21, 0xbfb8aa3b, v21
	v_mul_f32_e32 v22, 0xbfb8aa3b, v22
	v_mul_f32_e32 v23, 0xbfb8aa3b, v23
	v_ashrrev_i32_e32 v49, 31, v48
	v_exp_f32_e32 v28, v28
	v_exp_f32_e32 v29, v29
	v_exp_f32_e32 v30, v30
	v_exp_f32_e32 v31, v31
	v_exp_f32_e32 v20, v20
	v_exp_f32_e32 v21, v21
	v_exp_f32_e32 v22, v22
	v_exp_f32_e32 v23, v23
	v_mul_lo_u32 v50, s18, v49
	v_mul_lo_u32 v51, s19, v48
	v_mad_u64_u32 v[48:49], s[4:5], s18, v48, 0
	v_add3_u32 v49, v49, v50, v51
	v_lshl_add_u64 v[48:49], v[48:49], 1, s[8:9]
	v_pk_mul_f32 v[42:43], v[42:43], v[46:47]
	v_pk_mul_f32 v[40:41], v[40:41], v[44:45]
	v_pk_mul_f32 v[38:39], v[34:35], v[38:39]
	v_pk_mul_f32 v[34:35], v[32:33], v[36:37]
	v_lshl_add_u64 v[48:49], v[48:49], 0, v[112:113]
	v_cvt_pk_bf16_f32 v32, v40, v41
	v_cvt_pk_bf16_f32 v33, v42, v43
	v_cvt_pk_bf16_f32 v34, v34, v35
	v_cvt_pk_bf16_f32 v35, v38, v39
	v_add_f32_e32 v28, 1.0, v28
	v_add_f32_e32 v29, 1.0, v29
	v_add_f32_e32 v30, 1.0, v30
	v_add_f32_e32 v31, 1.0, v31
	v_add_f32_e32 v20, 1.0, v20
	v_add_f32_e32 v21, 1.0, v21
	v_add_f32_e32 v22, 1.0, v22
	v_add_f32_e32 v23, 1.0, v23
	global_store_dwordx4 v[48:49], v[32:35], off nt
	v_rcp_f32_e32 v28, v28
	v_rcp_f32_e32 v29, v29
	v_add_u32_e32 v32, 0xa0, v155
	v_rcp_f32_e32 v30, v30
	v_rcp_f32_e32 v31, v31
	v_rcp_f32_e32 v20, v20
	v_rcp_f32_e32 v22, v22
	v_rcp_f32_e32 v23, v23
	v_rcp_f32_e32 v21, v21
	v_mul_f32_e32 v12, 0xbfb8aa3b, v12
	v_mul_f32_e32 v13, 0xbfb8aa3b, v13
	v_mul_f32_e32 v14, 0xbfb8aa3b, v14
	v_mul_f32_e32 v15, 0xbfb8aa3b, v15
	v_mul_f32_e32 v8, 0xbfb8aa3b, v8
	v_mul_f32_e32 v9, 0xbfb8aa3b, v9
	v_mul_f32_e32 v10, 0xbfb8aa3b, v10
	v_mul_f32_e32 v11, 0xbfb8aa3b, v11
	v_ashrrev_i32_e32 v33, 31, v32
	v_exp_f32_e32 v12, v12
	v_exp_f32_e32 v13, v13
	v_exp_f32_e32 v14, v14
	v_exp_f32_e32 v15, v15
	v_exp_f32_e32 v8, v8
	v_exp_f32_e32 v9, v9
	v_exp_f32_e32 v10, v10
	v_exp_f32_e32 v11, v11
	v_mul_lo_u32 v34, s18, v33
	v_mul_lo_u32 v35, s19, v32
	v_mad_u64_u32 v[32:33], s[4:5], s18, v32, 0
	v_add3_u32 v33, v33, v34, v35
	v_lshl_add_u64 v[32:33], v[32:33], 1, s[8:9]
	v_pk_mul_f32 v[26:27], v[26:27], v[30:31]
	v_pk_mul_f32 v[24:25], v[24:25], v[28:29]
	v_pk_mul_f32 v[22:23], v[18:19], v[22:23]
	v_pk_mul_f32 v[18:19], v[16:17], v[20:21]
	v_lshl_add_u64 v[32:33], v[32:33], 0, v[112:113]
	v_cvt_pk_bf16_f32 v16, v24, v25
	v_cvt_pk_bf16_f32 v17, v26, v27
	v_cvt_pk_bf16_f32 v18, v18, v19
	v_cvt_pk_bf16_f32 v19, v22, v23
	v_add_f32_e32 v12, 1.0, v12
	v_add_f32_e32 v13, 1.0, v13
	v_add_f32_e32 v14, 1.0, v14
	v_add_f32_e32 v15, 1.0, v15
	v_add_f32_e32 v8, 1.0, v8
	v_add_f32_e32 v9, 1.0, v9
	v_add_f32_e32 v10, 1.0, v10
	v_add_f32_e32 v11, 1.0, v11
	global_store_dwordx4 v[32:33], v[16:19], off nt
	v_rcp_f32_e32 v12, v12
	v_rcp_f32_e32 v13, v13
	v_add_u32_e32 v16, 0xb0, v155
	v_rcp_f32_e32 v14, v14
	v_rcp_f32_e32 v15, v15
	v_rcp_f32_e32 v8, v8
	v_rcp_f32_e32 v10, v10
	v_rcp_f32_e32 v11, v11
	v_rcp_f32_e32 v9, v9
	v_ashrrev_i32_e32 v17, 31, v16
	v_mul_lo_u32 v18, s18, v17
	v_mul_lo_u32 v19, s19, v16
	v_mad_u64_u32 v[16:17], s[4:5], s18, v16, 0
	v_add3_u32 v17, v17, v18, v19
	v_lshl_add_u64 v[16:17], v[16:17], 1, s[8:9]
	v_pk_mul_f32 v[6:7], v[6:7], v[14:15]
	v_pk_mul_f32 v[4:5], v[4:5], v[12:13]
	v_pk_mul_f32 v[10:11], v[2:3], v[10:11]
	v_pk_mul_f32 v[2:3], v[0:1], v[8:9]
	v_lshl_add_u64 v[16:17], v[16:17], 0, v[112:113]
	v_cvt_pk_bf16_f32 v0, v4, v5
	v_cvt_pk_bf16_f32 v1, v6, v7
	v_cvt_pk_bf16_f32 v2, v2, v3
	v_cvt_pk_bf16_f32 v3, v10, v11
	global_store_dwordx4 v[16:17], v[0:3], off nt
